# wave reductions without LDS round trips: norm-phase wave_sum and ret_out sum16 butterflies use DPP adds and permlane swaps instead of ds_bpermute (same pairing order, bit-identical)
# baseline (speedup 1.0000x reference)
; #define LAS __attribute__((address_space(3)))
; __device__ __forceinline__ void ret_prefetch(const Frame& F, int it, int nchu, RetPre& P) {
;     const int bh = it / nchu, mc = it - bh * nchu + (NCH - nchu), h = bh & 7, b = bh >> 3;
;     const int tid = F.tid;
;     const size_t rowbase = (size_t)b * TB + 128 * mc;
; #pragma unroll
;     for (int i = 0; i < 2; ++i) {
;         const int u = tid + i * NTHREADS, r = u >> 3, c8 = (u & 7) * 8;
;         P.k[i] = *(const u32x4*)(WSB(WS_KN) + (rowbase + r) * 512 + h * 64 + c8);
;         P.sf[i] = *(const u32x4*)(WSB(WS_ST) + ((((size_t)(b * NH + h) * 2 + 0) * NCH + mc) * DV + r) * DK + c8);
;         P.sb[i] = *(const u32x4*)(WSB(WS_ST) + ((((size_t)(b * NH + h) * 2 + 1) * NCH + mc) * DV + r) * DK + c8);
;     }
; #pragma unroll
;     for (int i = 0; i < 4; ++i) {
;         const int u = tid + i * NTHREADS, r = u >> 4, c8 = (u & 15) * 8;
;         P.vt[i] = *(const u32x4*)(WSB(WS_VT) + ((size_t)(b * NH + h) * DV + r) * TB + 128 * mc + c8);
;     }
; __device__ __forceinline__ void ret_out_phase(const Args& A, Frame& F, int l, bool lastl, bf16_t* ARET, bf16_t* ALRU) {
;     ...
;     for (int jx = 0; jx < nmy; ++jx) {
;         const int it = F.bid + jx * F.G, itn = (jx + 1 < nmy) ? it + F.G : it;
;         const int bh = it / NCHU, mc = it - bh * NCHU + (NCH - NCHU), h = bh & 7, b = bh >> 3;
;         const size_t rowbase = (size_t)b * TB + 128 * mc;
;         __syncthreads();
; #pragma unroll
;         for (int i = 0; i < 2; ++i) {
;             const int u = tid + i * NTHREADS, r = u >> 3, c8 = (u & 7) * 8;
;             *(LAS u32x4*)(ks_ + r * 72 + c8) = P.k[i]; *(LAS u32x4*)(sfs + r * 72 + c8) = P.sf[i]; *(LAS u32x4*)(sbs + r * 72 + c8) = P.sb[i];
;         }
; #pragma unroll
;         for (int i = 0; i < 4; ++i) { const int u = tid + i * NTHREADS, r = u >> 4, c8 = (u & 15) * 8; *(LAS u32x4*)(vts + r * 136 + c8) = P.vt[i]; }
;         bf16x8 qf[2];
; #pragma unroll
;         for (int ks = 0; ks < 2; ++ks) qf[ks] = *(const bf16x8*)(WSB(WS_Q) + (rowbase + 16 * w + fr) * 512 + h * 64 + 32 * ks + 8 * fq);
;         __syncthreads();
;         ret_prefetch(F, itn, NCHU, P);
.LBB0_30:
	s_add_i32 s39, s39, 1
	s_cmp_lt_i32 s39, s37
	s_cselect_b32 s2, s34, 0
	s_abs_i32 s5, vcc_hi
	s_mul_hi_u32 s8, s5, s45
	s_mul_i32 s9, s8, s20
	s_sub_i32 s5, s5, s9
	s_ashr_i32 s4, vcc_hi, 31
	s_add_i32 s9, s8, 1
	s_sub_i32 s25, s5, s20
	s_cmp_ge_u32 s5, s20
	s_cselect_b32 s8, s9, s8
	s_cselect_b32 s5, s25, s5
	s_add_i32 s9, s8, 1
	s_cmp_ge_u32 s5, s20
	s_cselect_b32 s5, s9, s8
	s_xor_b32 s5, s5, s4
	s_sub_i32 s4, s5, s4
	s_not_b32 s5, s4
	s_mul_i32 s5, vcc_lo, s5
	s_ashr_i32 s8, s4, 3
	s_add_i32 s5, s61, s5
	s_ashr_i32 s9, s5, 31
	s_add_i32 s25, s2, vcc_hi
	s_mul_hi_i32 s52, s8, 0x900
	s_mulk_i32 s8, 0x900
	s_and_b32 s2, s4, 7
	s_add_u32 s8, s8, s5
	s_addc_u32 s9, s52, s9
	s_abs_i32 s5, s25
	s_mul_hi_u32 s52, s5, s45
	s_mul_i32 s53, s52, s20
	s_sub_i32 s5, s5, s53
	s_lshl_b32 s82, s2, 7
	s_ashr_i32 s4, s25, 31
	s_add_i32 s53, s52, 1
	s_sub_i32 s58, s5, s20
	s_cmp_ge_u32 s5, s20
	s_cselect_b32 s52, s53, s52
	s_cselect_b32 s5, s58, s5
	s_add_i32 s53, s52, 1
	s_cmp_ge_u32 s5, s20
	s_cselect_b32 s5, s53, s52
	s_xor_b32 s5, s5, s4
	s_sub_i32 s4, s5, s4
	s_not_b32 s5, s4
	s_mul_i32 s5, s20, s5
	s_add_i32 s5, s25, s5
	v_lshl_add_u64 v[50:51], v[122:123], 0, s[8:9]
	v_lshlrev_b64 v[50:51], 10, v[50:51]
	v_lshl_add_u64 v[50:51], s[48:49], 0, v[50:51]
	v_lshl_add_u64 v[50:51], v[50:51], 0, s[82:83]
	v_lshl_add_u64 v[50:51], v[50:51], 0, v[0:1]
	global_load_dwordx4 v[46:49], v[50:51], off
	global_load_dwordx4 v[42:45], v[50:51], off offset:64
	s_barrier
	s_waitcnt vmcnt(0)
	ds_write_b128 v134, v[6:9]
	ds_write_b128 v134, v[10:13] offset:53248
	ds_write_b128 v135, v[2:5]
	ds_write_b128 v136, v[22:25]
	ds_write_b128 v136, v[26:29] offset:53248
	ds_write_b128 v137, v[34:37]
	v_lshl_add_u64 v[2:3], v[122:123], 0, s[8:9]
	s_add_i32 s25, s5, 18
	v_lshlrev_b64 v[2:3], 10, v[2:3]
	s_ashr_i32 s5, s4, 3
	s_lshl_b32 s72, s25, 7
	v_lshl_add_u64 v[2:3], s[48:49], 0, v[2:3]
	s_mul_hi_i32 s52, s5, 0x900
	s_mulk_i32 s5, 0x900
	s_ashr_i32 s73, s72, 31
	v_lshl_add_u64 v[2:3], v[2:3], 0, s[82:83]
	s_add_u32 s92, s5, s72
	ds_write_b128 v245, v[14:17] offset:18432
	ds_write_b128 v246, v[18:21] offset:18432
	ds_write_b128 v247, v[30:33] offset:18432
	ds_write_b128 v248, v[38:41] offset:18432
	v_lshl_add_u64 v[2:3], v[2:3], 0, v[0:1]
	s_addc_u32 s93, s52, s73
	s_ashr_i32 s5, s4, 31
	s_mul_i32 s52, s4, 36
	s_ashr_i32 s58, s25, 31
	s_mul_hi_i32 s53, s4, 36
	s_add_u32 s52, s52, s25
	v_lshl_add_u64 v[2:3], s[92:93], 0, v[116:117]
	v_lshl_add_u64 v[14:15], s[92:93], 0, v[114:115]
	s_addc_u32 s53, s53, s58
	v_lshlrev_b64 v[2:3], 10, v[2:3]
	s_lshl_b32 s25, s4, 7
	v_lshlrev_b64 v[14:15], 10, v[14:15]
	s_lshl_b64 s[52:53], s[52:53], 14
	v_lshl_add_u64 v[2:3], s[6:7], 0, v[2:3]
	s_and_b32 s78, s25, 0x380
	s_mov_b32 s79, s83
	v_lshl_add_u64 v[14:15], s[6:7], 0, v[14:15]
	v_lshl_add_u64 v[2:3], v[2:3], 0, s[78:79]
	v_mov_b32_e32 v129, v1
	s_add_u32 s76, s62, s52
	v_lshl_add_u64 v[14:15], v[14:15], 0, s[78:79]
	v_lshl_add_u64 v[2:3], v[2:3], 0, v[128:129]
	s_addc_u32 s77, s63, s53
	v_lshl_add_u64 v[14:15], v[14:15], 0, v[128:129]
	s_waitcnt lgkmcnt(0)
	s_barrier
	global_load_dwordx4 v[6:9], v[2:3], off
	global_load_dwordx4 v[22:25], v[14:15], off
	v_lshl_add_u64 v[2:3], s[76:77], 0, v[120:121]
	s_add_u32 s74, s65, s52
	v_lshl_add_u64 v[14:15], s[76:77], 0, v[118:119]
	v_lshl_add_u64 v[2:3], v[2:3], 0, v[128:129]
	s_addc_u32 s75, s19, s53
	v_lshl_add_u64 v[14:15], v[14:15], 0, v[128:129]
	global_load_dwordx4 v[10:13], v[2:3], off
	global_load_dwordx4 v[26:29], v[14:15], off
	v_lshl_add_u64 v[2:3], s[74:75], 0, v[120:121]
	v_lshl_add_u64 v[14:15], s[74:75], 0, v[118:119]
	v_lshl_add_u64 v[2:3], v[2:3], 0, v[128:129]
	v_lshl_add_u64 v[14:15], v[14:15], 0, v[128:129]
	s_lshl_b64 s[74:75], s[4:5], 7
	global_load_dwordx4 v[2:5], v[2:3], off
	v_mov_b64_e32 v[38:39], s[54:55]
	global_load_dwordx4 v[34:37], v[14:15], off
	v_lshl_add_u64 v[14:15], s[74:75], 0, v[106:107]
	v_lshl_add_u64 v[18:19], s[74:75], 0, v[108:109]
	v_lshl_add_u64 v[30:31], s[74:75], 0, v[110:111]
	v_lshl_add_u64 v[50:51], s[74:75], 0, v[112:113]
	v_mad_u64_u32 v[16:17], s[4:5], v14, s96, v[38:39]
	v_mad_u64_u32 v[20:21], s[52:53], v18, s96, v[38:39]
	v_mad_u64_u32 v[32:33], s[52:53], v30, s96, v[38:39]
	v_mad_u64_u32 v[38:39], s[52:53], v50, s96, v[38:39]
	s_load_dwordx2 s[74:75], s[46:47], 0x60
	v_mad_i32_i24 v17, v15, s96, v17
	s_lshl_b64 s[4:5], s[72:73], 1
	v_mad_i32_i24 v21, v19, s96, v21
	v_mad_i32_i24 v33, v31, s96, v33
	v_mad_i32_i24 v39, v51, s96, v39
	v_lshl_add_u64 v[14:15], v[16:17], 0, s[4:5]
	v_lshl_add_u64 v[18:19], v[20:21], 0, s[4:5]
	v_lshl_add_u64 v[30:31], v[32:33], 0, s[4:5]
	v_lshl_add_u64 v[38:39], v[38:39], 0, s[4:5]
	s_or_b32 s4, s2, s64
	s_ashr_i32 s5, s4, 31
	s_lshl_b64 s[4:5], s[4:5], 2
	s_waitcnt lgkmcnt(0)
	s_add_u32 s78, s74, s4
	s_addc_u32 s79, s75, s5
	s_load_dword s98, s[78:79], 0x0
	s_load_dword s99, s[78:79], 0x20
	s_mov_b32 s76, 0xb2a5705f
	s_mov_b32 s77, 0x42ce8ed0
	s_mov_b32 s58, 0xc2b17218
	s_mov_b32 s25, 0x3f2aaaab
	s_mov_b32 s72, 0x7f800000
	s_mov_b32 s73, 0x33800000
	v_lshlrev_b32_e32 v40, 1, v104
	v_mov_b32_e32 v41, v1
	v_lshl_add_u64 v[14:15], v[14:15], 0, v[40:41]
	v_lshl_add_u64 v[18:19], v[18:19], 0, v[40:41]
	v_lshl_add_u64 v[30:31], v[30:31], 0, v[40:41]
	v_lshl_add_u64 v[38:39], v[38:39], 0, v[40:41]
	global_load_dwordx4 v[14:17], v[14:15], off
	v_readlane_b32 s4, v254, 38
	global_load_dwordx4 v[18:21], v[18:19], off
	v_readlane_b32 s5, v254, 39
	global_load_dwordx4 v[30:33], v[30:31], off
	v_add_u32_e32 v82, 0x4800, v230
	global_load_dwordx4 v[38:41], v[38:39], off
	s_mov_b32 s53, s64
	s_waitcnt vmcnt(10) lgkmcnt(0)
; #define LAS __attribute__((address_space(3)))
; __device__ __forceinline__ unsigned pk2(float lo, float hi) { const f32x2_t v = {lo, hi}; const bf16v2_t b = __builtin_convertvector(v, bf16v2_t); return __builtin_bit_cast(unsigned, b); }
; __device__ __forceinline__ float softplusf_(float x) { return fmaxf(x, 0.f) + log1pf(expf(-fabsf(x))); }
; __device__ __forceinline__ float log2_gamma(const Args& A, const Frame& F, int l, int dir, int h) {
;     const float x = GIN(12)[(l * 2 + dir) * NH + h];
;     return -softplusf_(-x) * 1.4426950408889634f;
; }
; __device__ __forceinline__ void ret_out_phase(const Args& A, Frame& F, int l, bool lastl, bf16_t* ARET, bf16_t* ALRU) {
;     ...
;         const float l2f = log2_gamma(A, F, l, 0, h), l2b = log2_gamma(A, F, l, 1, h);
;         bf16x8 pa[4];
;         {
;             const int i_loc = 16 * w + fr;
; #pragma unroll
;             for (int jp = 0; jp < 4; ++jp) {
;                 f32x4 c0 = (f32x4){0.f, 0.f, 0.f, 0.f}, c1 = c0;
; #pragma unroll
;                 for (int ks = 0; ks < 2; ++ks) {
;                     const bf16x8 k0 = *(const LAS bf16x8*)(ks_ + (32 * jp + fr) * 72 + 32 * ks + 8 * fq);
;                     const bf16x8 k1 = *(const LAS bf16x8*)(ks_ + (32 * jp + 16 + fr) * 72 + 32 * ks + 8 * fq);
;                     c0 = __builtin_amdgcn_mfma_f32_16x16x32_bf16(k0, qf[ks], c0, 0, 0, 0);
;                     c1 = __builtin_amdgcn_mfma_f32_16x16x32_bf16(k1, qf[ks], c1, 0, 0, 0);
;                 }
;                 float v[8];
; #pragma unroll
;                 for (int r = 0; r < 4; ++r) {
;                     const int j0 = 32 * jp + 4 * fq + r, j1 = j0 + 16;
;                     const int d0 = i_loc - j0, d1 = i_loc - j1;
;                     v[r] = c0[r] * (d0 >= 0 ? exp2f((float)d0 * l2f) : exp2f((float)(-d0) * l2b));
;                     v[4 + r] = c1[r] * (d1 >= 0 ? exp2f((float)d1 * l2f) : exp2f((float)(-d1) * l2b));
;                 }
;                 u32x4 pv; pv[0] = pk2(v[0], v[1]); pv[1] = pk2(v[2], v[3]); pv[2] = pk2(v[4], v[5]); pv[3] = pk2(v[6], v[7]);
;                 pa[jp] = __builtin_bit_cast(bf16x8, pv);
;             }
	s_mov_b32 s100, 0x3c800000
	v_mov_b32_e32 v50, s98
	v_and_b32_e32 v51, 0x7fffffff, v50
	v_mul_f32_e32 v51, 0xbfb8aa3b, v51
	v_exp_f32_e32 v51, v51
	v_mov_b32_e32 v52, 0x3e4ccccd
	v_fmaak_f32 v52, v51, v52, 0xbe800000
	v_fmaak_f32 v52, v51, v52, 0x3eaaaaab
	v_fmaak_f32 v52, v51, v52, 0xbf000000
	v_fmaak_f32 v52, v51, v52, 0x3f800000
	v_mul_f32_e32 v52, v51, v52
	v_add_f32_e32 v53, 1.0, v51
	v_log_f32_e32 v53, v53
	v_cmp_gt_f32_e64 s[74:75], s100, v51
	v_mul_f32_e32 v53, 0x3f317218, v53
	s_nop 1
	v_cndmask_b32_e64 v52, v53, v52, s[74:75]
	v_max_f32_e64 v53, -v50, 0
	v_add_f32_e32 v52, v53, v52
	v_mul_f32_e32 v66, 0xbfb8aa3b, v52
	v_mov_b32_e32 v54, s99
	v_and_b32_e32 v55, 0x7fffffff, v54
	v_mul_f32_e32 v55, 0xbfb8aa3b, v55
	v_exp_f32_e32 v55, v55
	v_mov_b32_e32 v56, 0x3e4ccccd
	v_fmaak_f32 v56, v55, v56, 0xbe800000
	v_fmaak_f32 v56, v55, v56, 0x3eaaaaab
	v_fmaak_f32 v56, v55, v56, 0xbf000000
	v_fmaak_f32 v56, v55, v56, 0x3f800000
	v_mul_f32_e32 v56, v55, v56
	v_add_f32_e32 v57, 1.0, v55
	v_log_f32_e32 v57, v57
	v_cmp_gt_f32_e64 s[74:75], s100, v55
	v_mul_f32_e32 v57, 0x3f317218, v57
	s_nop 1
	v_cndmask_b32_e64 v56, v57, v56, s[74:75]
	v_max_f32_e64 v57, -v54, 0
	v_add_f32_e32 v56, v57, v56
	v_mul_f32_e32 v67, 0xbfb8aa3b, v56
	ds_read_b128 v[50:53], v143
	ds_read_b128 v[54:57], v143 offset:2304
	s_waitcnt lgkmcnt(1)
	v_mfma_f32_16x16x32_bf16 v[50:53], v[50:53], v[46:49], 0
	ds_read_b128 v[58:61], v143 offset:64
	ds_read_b128 v[62:65], v143 offset:2368
	s_waitcnt lgkmcnt(1)
	v_mfma_f32_16x16x32_bf16 v[50:53], v[58:61], v[42:45], v[50:53]
	v_mul_f32_e32 v58, v67, v144
	v_mul_f32_e32 v59, v66, v145
	v_cndmask_b32_e64 v58, v59, v58, s[4:5]
	v_cmp_gt_f32_e64 s[74:75], s3, v58
	v_readlane_b32 s4, v254, 36
	v_mul_f32_e32 v60, v66, v147
	v_cndmask_b32_e64 v59, 0, v183, s[74:75]
	v_add_f32_e32 v58, v58, v59
	v_exp_f32_e32 v58, v58
	v_cndmask_b32_e64 v59, 0, v184, s[74:75]
	v_readlane_b32 s5, v254, 37
	v_mul_f32_e32 v61, v67, v148
	v_ldexp_f32 v58, v58, v59
	v_mul_f32_e32 v59, v67, v146
	v_cndmask_b32_e64 v59, v60, v59, s[4:5]
	v_cmp_gt_f32_e64 s[74:75], s3, v59
	v_readlane_b32 s4, v254, 40
	v_readlane_b32 s5, v254, 41
	v_cndmask_b32_e64 v60, 0, v183, s[74:75]
	v_add_f32_e32 v59, v59, v60
	v_exp_f32_e32 v59, v59
	v_cndmask_b32_e64 v60, 0, v184, s[74:75]
	v_mfma_f32_16x16x32_bf16 v[54:57], v[54:57], v[46:49], 0
	v_ldexp_f32 v60, v59, v60
	v_mul_f32_e32 v59, v66, v149
	v_cndmask_b32_e64 v59, v59, v61, s[4:5]
	v_cmp_gt_f32_e64 s[74:75], s3, v59
	v_readlane_b32 s4, v254, 42
	v_readlane_b32 s5, v254, 43
	v_cndmask_b32_e64 v61, 0, v183, s[74:75]
	v_add_f32_e32 v59, v59, v61
	v_exp_f32_e32 v59, v59
	v_cndmask_b32_e64 v61, 0, v184, s[74:75]
	s_waitcnt lgkmcnt(0)
	v_mfma_f32_16x16x32_bf16 v[54:57], v[62:65], v[42:45], v[54:57]
	v_ldexp_f32 v59, v59, v61
	v_pk_mul_f32 v[50:51], v[50:51], v[58:59]
	v_mul_f32_e32 v58, v66, v151
	v_mul_f32_e32 v59, v67, v150
	v_cndmask_b32_e64 v58, v58, v59, s[4:5]
	v_cmp_gt_f32_e64 s[74:75], s3, v58
	v_readlane_b32 s4, v254, 44
	v_readlane_b32 s5, v254, 45
	v_cndmask_b32_e64 v59, 0, v183, s[74:75]
	v_add_f32_e32 v58, v58, v59
	v_exp_f32_e32 v58, v58
	v_cndmask_b32_e64 v59, 0, v184, s[74:75]
	v_cvt_pk_bf16_f32 v50, v50, v51
	v_ldexp_f32 v61, v58, v59
	v_mul_f32_e32 v58, v66, v153
	v_mul_f32_e32 v59, v67, v152
	v_cndmask_b32_e64 v58, v58, v59, s[4:5]
	v_cmp_gt_f32_e64 s[74:75], s3, v58
	v_readlane_b32 s4, v254, 46
	v_pk_mul_f32 v[54:55], v[54:55], v[60:61]
	v_cndmask_b32_e64 v59, 0, v183, s[74:75]
	v_add_f32_e32 v58, v58, v59
	v_exp_f32_e32 v58, v58
	v_cndmask_b32_e64 v59, 0, v184, s[74:75]
	v_mul_f32_e32 v60, v67, v154
	v_readlane_b32 s5, v254, 47
	v_ldexp_f32 v58, v58, v59
	v_mul_f32_e32 v59, v66, v155
	v_cndmask_b32_e64 v59, v59, v60, s[4:5]
	v_cmp_gt_f32_e64 s[74:75], s3, v59
	v_readlane_b32 s4, v254, 48
	v_mul_f32_e32 v61, v67, v156
	v_cndmask_b32_e64 v60, 0, v183, s[74:75]
	v_add_f32_e32 v59, v59, v60
	v_exp_f32_e32 v59, v59
	v_cndmask_b32_e64 v60, 0, v184, s[74:75]
	v_readlane_b32 s5, v254, 49
	v_ldexp_f32 v60, v59, v60
	v_mul_f32_e32 v59, v66, v157
	v_cndmask_b32_e64 v59, v59, v61, s[4:5]
	v_cmp_gt_f32_e64 s[74:75], s3, v59
	v_readlane_b32 s4, v254, 50
	v_readlane_b32 s5, v254, 51
	v_cndmask_b32_e64 v61, 0, v183, s[74:75]
	v_add_f32_e32 v59, v59, v61
	v_exp_f32_e32 v59, v59
	v_cndmask_b32_e64 v61, 0, v184, s[74:75]
	v_ldexp_f32 v59, v59, v61
	v_pk_mul_f32 v[52:53], v[52:53], v[58:59]
	v_mul_f32_e32 v58, v66, v159
	v_mul_f32_e32 v59, v67, v158
	v_cndmask_b32_e64 v58, v58, v59, s[4:5]
	v_cmp_gt_f32_e64 s[74:75], s3, v58
	v_cvt_pk_bf16_f32 v51, v52, v53
	v_cvt_pk_bf16_f32 v52, v54, v55
	v_cndmask_b32_e64 v59, 0, v183, s[74:75]
	v_add_f32_e32 v58, v58, v59
	v_exp_f32_e32 v58, v58
	v_cndmask_b32_e64 v59, 0, v184, s[74:75]
	v_readlane_b32 s4, v254, 52
	v_readlane_b32 s5, v254, 53
	v_ldexp_f32 v61, v58, v59
	v_pk_mul_f32 v[56:57], v[56:57], v[60:61]
	s_nop 0
	v_cvt_pk_bf16_f32 v53, v56, v57
	ds_read_b128 v[54:57], v160
	ds_read_b128 v[58:61], v160 offset:2304
	s_waitcnt lgkmcnt(1)
	v_mfma_f32_16x16x32_bf16 v[54:57], v[54:57], v[46:49], 0
	ds_read_b128 v[62:65], v160 offset:64
	ds_read_b128 v[68:71], v160 offset:2368
	s_waitcnt lgkmcnt(1)
; #define LAS __attribute__((address_space(3)))
; __device__ __forceinline__ unsigned pk2(float lo, float hi) { const f32x2_t v = {lo, hi}; const bf16v2_t b = __builtin_convertvector(v, bf16v2_t); return __builtin_bit_cast(unsigned, b); }
; __device__ __forceinline__ void ret_out_phase(const Args& A, Frame& F, int l, bool lastl, bf16_t* ARET, bf16_t* ALRU) {
;     ...
;             for (int jp = 0; jp < 4; ++jp) {
;                 f32x4 c0 = (f32x4){0.f, 0.f, 0.f, 0.f}, c1 = c0;
; #pragma unroll
;                 for (int ks = 0; ks < 2; ++ks) {
;                     const bf16x8 k0 = *(const LAS bf16x8*)(ks_ + (32 * jp + fr) * 72 + 32 * ks + 8 * fq);
;                     const bf16x8 k1 = *(const LAS bf16x8*)(ks_ + (32 * jp + 16 + fr) * 72 + 32 * ks + 8 * fq);
;                     c0 = __builtin_amdgcn_mfma_f32_16x16x32_bf16(k0, qf[ks], c0, 0, 0, 0);
;                     c1 = __builtin_amdgcn_mfma_f32_16x16x32_bf16(k1, qf[ks], c1, 0, 0, 0);
;                 }
;                 float v[8];
; #pragma unroll
;                 for (int r = 0; r < 4; ++r) {
;                     const int j0 = 32 * jp + 4 * fq + r, j1 = j0 + 16;
;                     const int d0 = i_loc - j0, d1 = i_loc - j1;
;                     v[r] = c0[r] * (d0 >= 0 ? exp2f((float)d0 * l2f) : exp2f((float)(-d0) * l2b));
;                     v[4 + r] = c1[r] * (d1 >= 0 ? exp2f((float)d1 * l2f) : exp2f((float)(-d1) * l2b));
;                 }
;                 u32x4 pv; pv[0] = pk2(v[0], v[1]); pv[1] = pk2(v[2], v[3]); pv[2] = pk2(v[4], v[5]); pv[3] = pk2(v[6], v[7]);
;                 pa[jp] = __builtin_bit_cast(bf16x8, pv);
;             }
	v_mfma_f32_16x16x32_bf16 v[54:57], v[62:65], v[42:45], v[54:57]
	v_mul_f32_e32 v62, v66, v162
	v_mul_f32_e32 v63, v67, v161
	v_cndmask_b32_e64 v62, v62, v63, s[4:5]
	v_cmp_gt_f32_e64 s[74:75], s3, v62
	v_readlane_b32 s4, v254, 54
	v_mul_f32_e32 v64, v67, v163
	v_cndmask_b32_e64 v63, 0, v183, s[74:75]
	v_add_f32_e32 v62, v62, v63
	v_exp_f32_e32 v62, v62
	v_cndmask_b32_e64 v63, 0, v184, s[74:75]
	v_readlane_b32 s5, v254, 55
	v_mul_f32_e32 v65, v67, v165
	v_ldexp_f32 v62, v62, v63
	v_mul_f32_e32 v63, v66, v164
	v_cndmask_b32_e64 v63, v63, v64, s[4:5]
	v_cmp_gt_f32_e64 s[74:75], s3, v63
	v_readlane_b32 s4, v254, 56
	v_readlane_b32 s5, v254, 57
	v_cndmask_b32_e64 v64, 0, v183, s[74:75]
	v_add_f32_e32 v63, v63, v64
	v_exp_f32_e32 v63, v63
	v_cndmask_b32_e64 v64, 0, v184, s[74:75]
	v_mfma_f32_16x16x32_bf16 v[58:61], v[58:61], v[46:49], 0
	v_ldexp_f32 v64, v63, v64
	v_mul_f32_e32 v63, v66, v166
	v_cndmask_b32_e64 v63, v63, v65, s[4:5]
	v_cmp_gt_f32_e64 s[74:75], s3, v63
	v_readlane_b32 s4, v254, 58
	v_readlane_b32 s5, v254, 59
	v_cndmask_b32_e64 v65, 0, v183, s[74:75]
	v_add_f32_e32 v63, v63, v65
	v_exp_f32_e32 v63, v63
	v_cndmask_b32_e64 v65, 0, v184, s[74:75]
	s_waitcnt lgkmcnt(0)
	v_mfma_f32_16x16x32_bf16 v[58:61], v[68:71], v[42:45], v[58:61]
	v_ldexp_f32 v63, v63, v65
	v_pk_mul_f32 v[54:55], v[54:55], v[62:63]
	v_mul_f32_e32 v62, v66, v168
	v_mul_f32_e32 v63, v67, v167
	v_cndmask_b32_e64 v62, v62, v63, s[4:5]
	v_cmp_gt_f32_e64 s[74:75], s3, v62
	v_readlane_b32 s4, v254, 60
	v_readlane_b32 s5, v254, 61
	v_cndmask_b32_e64 v63, 0, v183, s[74:75]
	v_add_f32_e32 v62, v62, v63
	v_exp_f32_e32 v62, v62
	v_cndmask_b32_e64 v63, 0, v184, s[74:75]
	v_cvt_pk_bf16_f32 v54, v54, v55
	v_ldexp_f32 v65, v62, v63
	v_mul_f32_e32 v62, v66, v189
	v_mul_f32_e32 v63, v67, v169
	v_cndmask_b32_e64 v62, v62, v63, s[4:5]
	v_cmp_gt_f32_e64 s[74:75], s3, v62
	v_readlane_b32 s4, v254, 62
	v_pk_mul_f32 v[58:59], v[58:59], v[64:65]
	v_cndmask_b32_e64 v63, 0, v183, s[74:75]
	v_add_f32_e32 v62, v62, v63
	v_exp_f32_e32 v62, v62
	v_cndmask_b32_e64 v63, 0, v184, s[74:75]
	v_mul_f32_e32 v64, v67, v190
	v_readlane_b32 s5, v254, 63
	v_ldexp_f32 v62, v62, v63
	v_mul_f32_e32 v63, v66, v191
	v_cndmask_b32_e64 v63, v63, v64, s[4:5]
	v_cmp_gt_f32_e64 s[74:75], s3, v63
	v_readlane_b32 s4, v255, 0
	v_mul_f32_e32 v65, v67, v192
	v_cndmask_b32_e64 v64, 0, v183, s[74:75]
	v_add_f32_e32 v63, v63, v64
	v_exp_f32_e32 v63, v63
	v_cndmask_b32_e64 v64, 0, v184, s[74:75]
	v_readlane_b32 s5, v255, 1
	v_ldexp_f32 v64, v63, v64
	v_mul_f32_e32 v63, v66, v193
	v_cndmask_b32_e64 v63, v63, v65, s[4:5]
	v_cmp_gt_f32_e64 s[74:75], s3, v63
	v_readlane_b32 s4, v255, 2
	v_readlane_b32 s5, v255, 3
	v_cndmask_b32_e64 v65, 0, v183, s[74:75]
	v_add_f32_e32 v63, v63, v65
	v_exp_f32_e32 v63, v63
	v_cndmask_b32_e64 v65, 0, v184, s[74:75]
	v_ldexp_f32 v63, v63, v65
	v_pk_mul_f32 v[56:57], v[56:57], v[62:63]
	v_mul_f32_e32 v62, v66, v195
	v_mul_f32_e32 v63, v67, v194
	v_cndmask_b32_e64 v62, v62, v63, s[4:5]
	v_cmp_gt_f32_e64 s[74:75], s3, v62
	v_cvt_pk_bf16_f32 v55, v56, v57
	v_cvt_pk_bf16_f32 v56, v58, v59
	v_cndmask_b32_e64 v63, 0, v183, s[74:75]
	v_add_f32_e32 v62, v62, v63
	v_exp_f32_e32 v62, v62
	v_cndmask_b32_e64 v63, 0, v184, s[74:75]
	v_readlane_b32 s4, v255, 4
	v_readlane_b32 s5, v255, 5
	v_ldexp_f32 v65, v62, v63
	v_pk_mul_f32 v[60:61], v[60:61], v[64:65]
	s_nop 0
	v_cvt_pk_bf16_f32 v57, v60, v61
	ds_read_b128 v[58:61], v196
	ds_read_b128 v[62:65], v196 offset:2304
	s_waitcnt lgkmcnt(1)
	v_mfma_f32_16x16x32_bf16 v[58:61], v[58:61], v[46:49], 0
	ds_read_b128 v[68:71], v196 offset:64
	ds_read_b128 v[72:75], v196 offset:2368
	s_waitcnt lgkmcnt(1)
	v_mfma_f32_16x16x32_bf16 v[58:61], v[68:71], v[42:45], v[58:61]
	v_mul_f32_e32 v68, v66, v198
	v_mul_f32_e32 v69, v67, v197
	v_cndmask_b32_e64 v68, v68, v69, s[4:5]
	v_cmp_gt_f32_e64 s[74:75], s3, v68
	v_readlane_b32 s4, v255, 6
	v_mul_f32_e32 v70, v67, v199
	v_cndmask_b32_e64 v69, 0, v183, s[74:75]
	v_add_f32_e32 v68, v68, v69
	v_exp_f32_e32 v68, v68
	v_cndmask_b32_e64 v69, 0, v184, s[74:75]
	v_readlane_b32 s5, v255, 7
	v_mul_f32_e32 v71, v67, v201
	v_ldexp_f32 v68, v68, v69
	v_mul_f32_e32 v69, v66, v200
	v_cndmask_b32_e64 v69, v69, v70, s[4:5]
	v_cmp_gt_f32_e64 s[74:75], s3, v69
	v_readlane_b32 s4, v255, 8
	v_readlane_b32 s5, v255, 9
	v_cndmask_b32_e64 v70, 0, v183, s[74:75]
	v_add_f32_e32 v69, v69, v70
	v_exp_f32_e32 v69, v69
	v_cndmask_b32_e64 v70, 0, v184, s[74:75]
	v_mfma_f32_16x16x32_bf16 v[62:65], v[62:65], v[46:49], 0
	v_ldexp_f32 v70, v69, v70
	v_mul_f32_e32 v69, v66, v202
	v_cndmask_b32_e64 v69, v69, v71, s[4:5]
	v_cmp_gt_f32_e64 s[74:75], s3, v69
	v_readlane_b32 s4, v255, 10
	v_readlane_b32 s5, v255, 11
	v_cndmask_b32_e64 v71, 0, v183, s[74:75]
	v_add_f32_e32 v69, v69, v71
	v_exp_f32_e32 v69, v69
	v_cndmask_b32_e64 v71, 0, v184, s[74:75]
	s_waitcnt lgkmcnt(0)
; #define LAS __attribute__((address_space(3)))
; __device__ __forceinline__ unsigned pk2(float lo, float hi) { const f32x2_t v = {lo, hi}; const bf16v2_t b = __builtin_convertvector(v, bf16v2_t); return __builtin_bit_cast(unsigned, b); }
; __device__ __forceinline__ void ret_out_phase(const Args& A, Frame& F, int l, bool lastl, bf16_t* ARET, bf16_t* ALRU) {
;     ...
;             for (int jp = 0; jp < 4; ++jp) {
;                 f32x4 c0 = (f32x4){0.f, 0.f, 0.f, 0.f}, c1 = c0;
; #pragma unroll
;                 for (int ks = 0; ks < 2; ++ks) {
;                     const bf16x8 k0 = *(const LAS bf16x8*)(ks_ + (32 * jp + fr) * 72 + 32 * ks + 8 * fq);
;                     const bf16x8 k1 = *(const LAS bf16x8*)(ks_ + (32 * jp + 16 + fr) * 72 + 32 * ks + 8 * fq);
;                     c0 = __builtin_amdgcn_mfma_f32_16x16x32_bf16(k0, qf[ks], c0, 0, 0, 0);
;                     c1 = __builtin_amdgcn_mfma_f32_16x16x32_bf16(k1, qf[ks], c1, 0, 0, 0);
;                 }
;                 float v[8];
; #pragma unroll
;                 for (int r = 0; r < 4; ++r) {
;                     const int j0 = 32 * jp + 4 * fq + r, j1 = j0 + 16;
;                     const int d0 = i_loc - j0, d1 = i_loc - j1;
;                     v[r] = c0[r] * (d0 >= 0 ? exp2f((float)d0 * l2f) : exp2f((float)(-d0) * l2b));
;                     v[4 + r] = c1[r] * (d1 >= 0 ? exp2f((float)d1 * l2f) : exp2f((float)(-d1) * l2b));
;                 }
;                 u32x4 pv; pv[0] = pk2(v[0], v[1]); pv[1] = pk2(v[2], v[3]); pv[2] = pk2(v[4], v[5]); pv[3] = pk2(v[6], v[7]);
;                 pa[jp] = __builtin_bit_cast(bf16x8, pv);
;             }
	v_mfma_f32_16x16x32_bf16 v[62:65], v[72:75], v[42:45], v[62:65]
	v_ldexp_f32 v69, v69, v71
	v_pk_mul_f32 v[58:59], v[58:59], v[68:69]
	v_mul_f32_e32 v68, v66, v204
	v_mul_f32_e32 v69, v67, v203
	v_cndmask_b32_e64 v68, v68, v69, s[4:5]
	v_cmp_gt_f32_e64 s[74:75], s3, v68
	v_readlane_b32 s4, v255, 12
	v_readlane_b32 s5, v255, 13
	v_cndmask_b32_e64 v69, 0, v183, s[74:75]
	v_add_f32_e32 v68, v68, v69
	v_exp_f32_e32 v68, v68
	v_cndmask_b32_e64 v69, 0, v184, s[74:75]
	v_cvt_pk_bf16_f32 v58, v58, v59
	v_ldexp_f32 v71, v68, v69
	v_mul_f32_e32 v68, v66, v206
	v_mul_f32_e32 v69, v67, v205
	v_cndmask_b32_e64 v68, v68, v69, s[4:5]
	v_cmp_gt_f32_e64 s[74:75], s3, v68
	v_readlane_b32 s4, v255, 14
	v_pk_mul_f32 v[62:63], v[62:63], v[70:71]
	v_cndmask_b32_e64 v69, 0, v183, s[74:75]
	v_add_f32_e32 v68, v68, v69
	v_exp_f32_e32 v68, v68
	v_cndmask_b32_e64 v69, 0, v184, s[74:75]
	v_mul_f32_e32 v70, v67, v207
	v_readlane_b32 s5, v255, 15
	v_ldexp_f32 v68, v68, v69
	v_mul_f32_e32 v69, v66, v208
	v_cndmask_b32_e64 v69, v69, v70, s[4:5]
	v_cmp_gt_f32_e64 s[74:75], s3, v69
	v_readlane_b32 s4, v255, 16
	v_mul_f32_e32 v71, v67, v209
	v_cndmask_b32_e64 v70, 0, v183, s[74:75]
	v_add_f32_e32 v69, v69, v70
	v_exp_f32_e32 v69, v69
	v_cndmask_b32_e64 v70, 0, v184, s[74:75]
	v_readlane_b32 s5, v255, 17
	v_ldexp_f32 v70, v69, v70
	v_mul_f32_e32 v69, v66, v210
	v_cndmask_b32_e64 v69, v69, v71, s[4:5]
	v_cmp_gt_f32_e64 s[74:75], s3, v69
	v_readlane_b32 s4, v255, 18
	v_readlane_b32 s5, v255, 19
	v_cndmask_b32_e64 v71, 0, v183, s[74:75]
	v_add_f32_e32 v69, v69, v71
	v_exp_f32_e32 v69, v69
	v_cndmask_b32_e64 v71, 0, v184, s[74:75]
	v_ldexp_f32 v69, v69, v71
	v_pk_mul_f32 v[60:61], v[60:61], v[68:69]
	v_mul_f32_e32 v68, v66, v212
	v_mul_f32_e32 v69, v67, v211
	v_cndmask_b32_e64 v68, v68, v69, s[4:5]
	v_cmp_gt_f32_e64 s[74:75], s3, v68
	v_cvt_pk_bf16_f32 v59, v60, v61
	v_cvt_pk_bf16_f32 v60, v62, v63
	v_cndmask_b32_e64 v69, 0, v183, s[74:75]
	v_add_f32_e32 v68, v68, v69
	v_exp_f32_e32 v68, v68
	v_cndmask_b32_e64 v69, 0, v184, s[74:75]
	v_readlane_b32 s4, v255, 20
	v_readlane_b32 s5, v255, 21
	v_ldexp_f32 v71, v68, v69
	v_pk_mul_f32 v[64:65], v[64:65], v[70:71]
	s_nop 0
	v_cvt_pk_bf16_f32 v61, v64, v65
	ds_read_b128 v[62:65], v213
	ds_read_b128 v[68:71], v213 offset:2304
	s_waitcnt lgkmcnt(1)
	v_mfma_f32_16x16x32_bf16 v[62:65], v[62:65], v[46:49], 0
	ds_read_b128 v[72:75], v213 offset:64
	ds_read_b128 v[76:79], v213 offset:2368
	s_waitcnt lgkmcnt(1)
	v_mfma_f32_16x16x32_bf16 v[62:65], v[72:75], v[42:45], v[62:65]
	v_mul_f32_e32 v72, v66, v215
	v_mul_f32_e32 v73, v67, v214
	v_cndmask_b32_e64 v72, v72, v73, s[4:5]
	v_cmp_gt_f32_e64 s[74:75], s3, v72
	v_readlane_b32 s4, v255, 22
	v_mul_f32_e32 v74, v67, v216
	v_cndmask_b32_e64 v73, 0, v183, s[74:75]
	v_add_f32_e32 v72, v72, v73
	v_exp_f32_e32 v72, v72
	v_cndmask_b32_e64 v73, 0, v184, s[74:75]
	v_readlane_b32 s5, v255, 23
	v_mul_f32_e32 v75, v67, v218
	v_ldexp_f32 v72, v72, v73
	v_mul_f32_e32 v73, v66, v217
	v_cndmask_b32_e64 v73, v73, v74, s[4:5]
	v_cmp_gt_f32_e64 s[74:75], s3, v73
	v_readlane_b32 s4, v255, 24
	v_readlane_b32 s5, v255, 25
	v_cndmask_b32_e64 v74, 0, v183, s[74:75]
	v_add_f32_e32 v73, v73, v74
	v_exp_f32_e32 v73, v73
	v_cndmask_b32_e64 v74, 0, v184, s[74:75]
	v_mfma_f32_16x16x32_bf16 v[68:71], v[68:71], v[46:49], 0
	v_ldexp_f32 v74, v73, v74
	v_mul_f32_e32 v73, v66, v219
	v_cndmask_b32_e64 v73, v73, v75, s[4:5]
	v_cmp_gt_f32_e64 s[74:75], s3, v73
	v_readlane_b32 s4, v255, 26
	v_readlane_b32 s5, v255, 27
	v_cndmask_b32_e64 v75, 0, v183, s[74:75]
	v_add_f32_e32 v73, v73, v75
	v_exp_f32_e32 v73, v73
	v_cndmask_b32_e64 v75, 0, v184, s[74:75]
	s_waitcnt lgkmcnt(0)
	v_mfma_f32_16x16x32_bf16 v[68:71], v[76:79], v[42:45], v[68:71]
	v_ldexp_f32 v73, v73, v75
	v_pk_mul_f32 v[62:63], v[62:63], v[72:73]
	v_mul_f32_e32 v72, v66, v221
	v_mul_f32_e32 v73, v67, v220
	v_cndmask_b32_e64 v72, v72, v73, s[4:5]
	v_cmp_gt_f32_e64 s[74:75], s3, v72
	v_readlane_b32 s4, v255, 28
	v_readlane_b32 s5, v255, 29
	v_cndmask_b32_e64 v73, 0, v183, s[74:75]
	v_add_f32_e32 v72, v72, v73
	v_exp_f32_e32 v72, v72
	v_cndmask_b32_e64 v73, 0, v184, s[74:75]
	v_cvt_pk_bf16_f32 v62, v62, v63
	v_ldexp_f32 v75, v72, v73
	v_mul_f32_e32 v72, v66, v223
	v_mul_f32_e32 v73, v67, v222
	v_cndmask_b32_e64 v72, v72, v73, s[4:5]
	v_cmp_gt_f32_e64 s[74:75], s3, v72
	v_pk_mul_f32 v[68:69], v[68:69], v[74:75]
	v_mul_f32_e32 v74, v67, v224
	v_cndmask_b32_e64 v73, 0, v183, s[74:75]
	v_add_f32_e32 v72, v72, v73
	v_exp_f32_e32 v72, v72
	v_cndmask_b32_e64 v73, 0, v184, s[74:75]
	v_mul_f32_e32 v75, v67, v226
	v_ldexp_f32 v72, v72, v73
	v_mul_f32_e32 v73, v66, v225
	v_cndmask_b32_e64 v73, v73, v74, s[66:67]
	v_cmp_gt_f32_e64 s[74:75], s3, v73
	s_nop 1
	v_cndmask_b32_e64 v74, 0, v183, s[74:75]
	v_add_f32_e32 v73, v73, v74
	v_exp_f32_e32 v73, v73
	v_cndmask_b32_e64 v74, 0, v184, s[74:75]
	v_ldexp_f32 v74, v73, v74
	v_mul_f32_e32 v73, v66, v227
	v_cndmask_b32_e64 v73, v73, v75, s[68:69]
	v_cmp_gt_f32_e64 s[74:75], s3, v73
	s_nop 1
	v_cndmask_b32_e64 v75, 0, v183, s[74:75]
	v_add_f32_e32 v73, v73, v75
	v_exp_f32_e32 v73, v73
	v_cndmask_b32_e64 v75, 0, v184, s[74:75]
	v_ldexp_f32 v73, v73, v75
	v_pk_mul_f32 v[64:65], v[64:65], v[72:73]
	v_mul_f32_e32 v72, v66, v229
	v_mul_f32_e32 v73, v67, v228
	v_cndmask_b32_e64 v72, v72, v73, s[70:71]
	v_cmp_gt_f32_e64 s[74:75], s3, v72
	v_cvt_pk_bf16_f32 v63, v64, v65
	v_cvt_pk_bf16_f32 v64, v68, v69
	v_cndmask_b32_e64 v73, 0, v183, s[74:75]
	v_mul_f32_e32 v68, v66, v103
	v_add_f32_e32 v72, v72, v73
	v_cndmask_b32_e64 v73, 0, v184, s[74:75]
	v_cmp_gt_f32_e64 s[74:75], s3, v68
	v_exp_f32_e32 v72, v72
	v_and_b32_e32 v69, 0xffff0000, v46
; #define LAS __attribute__((address_space(3)))
; __device__ __forceinline__ void ret_out_phase(const Args& A, Frame& F, int l, bool lastl, bf16_t* ARET, bf16_t* ALRU) {
;     ...
;         bf16x8 qF[2], qB[2];
;         {
;             const int il = 16 * w + fr;
;             const float sF = exp2f((float)(il + 1) * l2f), sB = exp2f((float)(128 - il) * l2b);
; #pragma unroll
;             for (int ks = 0; ks < 2; ++ks) { qF[ks] = scale1(qf[ks], sF); qB[ks] = scale1(qf[ks], sB); }
;         }
;         f32x4 O[8];
; #pragma unroll
;         for (int dvt = 0; dvt < 8; ++dvt) {
;             f32x4 o = (f32x4){0.f, 0.f, 0.f, 0.f};
; #pragma unroll
;             for (int jp = 0; jp < 4; ++jp) {
;                 const u32x2 lo = *(const LAS u32x2*)(vts + (16 * dvt + fr) * 136 + 32 * jp + 4 * fq);
;                 const u32x2 hi = *(const LAS u32x2*)(vts + (16 * dvt + fr) * 136 + 32 * jp + 16 + 4 * fq);
;                 u32x4 bv; bv[0] = lo.x; bv[1] = lo.y; bv[2] = hi.x; bv[3] = hi.y;
;                 o = __builtin_amdgcn_mfma_f32_16x16x32_bf16(pa[jp], __builtin_bit_cast(bf16x8, bv), o, 0, 0, 0);
;             }
; #pragma unroll
;             for (int ks = 0; ks < 2; ++ks) {
;                 const bf16x8 sf = *(const LAS bf16x8*)(sfs + (16 * dvt + fr) * 72 + 32 * ks + 8 * fq);
;                 const bf16x8 sb = *(const LAS bf16x8*)(sbs + (16 * dvt + fr) * 72 + 32 * ks + 8 * fq);
;                 o = __builtin_amdgcn_mfma_f32_16x16x32_bf16(qF[ks], sf, o, 0, 0, 0);
;                 o = __builtin_amdgcn_mfma_f32_16x16x32_bf16(qB[ks], sb, o, 0, 0, 0);
;             }
;             O[dvt] = o;
;             __builtin_amdgcn_sched_barrier(0);
;         }
	v_cndmask_b32_e64 v68, 0, v183, s[74:75]
	v_fmac_f32_e32 v68, v66, v103
	v_exp_f32_e32 v66, v68
	v_ldexp_f32 v75, v72, v73
	v_cndmask_b32_e64 v68, 0, v184, s[74:75]
	v_pk_mul_f32 v[70:71], v[70:71], v[74:75]
	v_ldexp_f32 v74, v66, v68
	v_mul_f32_e32 v66, v67, v105
	v_cmp_gt_f32_e64 s[74:75], s3, v66
	v_lshlrev_b32_e32 v68, 16, v46
	v_cvt_pk_bf16_f32 v65, v70, v71
	v_cndmask_b32_e64 v66, 0, v183, s[74:75]
	v_fmac_f32_e32 v66, v67, v105
	v_exp_f32_e32 v66, v66
	v_cndmask_b32_e64 v67, 0, v184, s[74:75]
	v_ldexp_f32 v76, v66, v67
	v_pk_mul_f32 v[66:67], v[74:75], v[68:69] op_sel_hi:[0,1]
	v_pk_mul_f32 v[68:69], v[76:77], v[68:69] op_sel_hi:[0,1]
	v_cvt_pk_bf16_f32 v46, v68, v69
	v_lshlrev_b32_e32 v68, 16, v47
	v_and_b32_e32 v69, 0xffff0000, v47
	v_pk_mul_f32 v[70:71], v[74:75], v[68:69] op_sel_hi:[0,1]
	v_cvt_pk_bf16_f32 v66, v66, v67
	v_cvt_pk_bf16_f32 v67, v70, v71
	v_pk_mul_f32 v[68:69], v[76:77], v[68:69] op_sel_hi:[0,1]
	v_lshlrev_b32_e32 v70, 16, v48
	v_and_b32_e32 v71, 0xffff0000, v48
	v_cvt_pk_bf16_f32 v47, v68, v69
	v_pk_mul_f32 v[68:69], v[74:75], v[70:71] op_sel_hi:[0,1]
	v_pk_mul_f32 v[70:71], v[76:77], v[70:71] op_sel_hi:[0,1]
	v_cvt_pk_bf16_f32 v48, v70, v71
	v_lshlrev_b32_e32 v70, 16, v49
	v_and_b32_e32 v71, 0xffff0000, v49
	v_pk_mul_f32 v[72:73], v[74:75], v[70:71] op_sel_hi:[0,1]
	v_cvt_pk_bf16_f32 v68, v68, v69
	v_cvt_pk_bf16_f32 v69, v72, v73
	v_pk_mul_f32 v[70:71], v[76:77], v[70:71] op_sel_hi:[0,1]
	v_lshlrev_b32_e32 v72, 16, v42
	v_and_b32_e32 v73, 0xffff0000, v42
	v_cvt_pk_bf16_f32 v49, v70, v71
	v_pk_mul_f32 v[70:71], v[74:75], v[72:73] op_sel_hi:[0,1]
	v_pk_mul_f32 v[72:73], v[76:77], v[72:73] op_sel_hi:[0,1]
	v_cvt_pk_bf16_f32 v42, v72, v73
	v_lshlrev_b32_e32 v72, 16, v43
	v_and_b32_e32 v73, 0xffff0000, v43
	v_pk_mul_f32 v[78:79], v[74:75], v[72:73] op_sel_hi:[0,1]
	v_cvt_pk_bf16_f32 v70, v70, v71
	v_cvt_pk_bf16_f32 v71, v78, v79
	v_pk_mul_f32 v[72:73], v[76:77], v[72:73] op_sel_hi:[0,1]
	v_lshlrev_b32_e32 v78, 16, v44
	v_and_b32_e32 v79, 0xffff0000, v44
	v_cvt_pk_bf16_f32 v43, v72, v73
	v_pk_mul_f32 v[72:73], v[74:75], v[78:79] op_sel_hi:[0,1]
	v_pk_mul_f32 v[78:79], v[76:77], v[78:79] op_sel_hi:[0,1]
	v_cvt_pk_bf16_f32 v44, v78, v79
	v_lshlrev_b32_e32 v78, 16, v45
	v_and_b32_e32 v79, 0xffff0000, v45
	v_pk_mul_f32 v[74:75], v[74:75], v[78:79] op_sel_hi:[0,1]
	v_cvt_pk_bf16_f32 v72, v72, v73
	v_cvt_pk_bf16_f32 v73, v74, v75
	v_pk_mul_f32 v[74:75], v[76:77], v[78:79] op_sel_hi:[0,1]
	v_cvt_pk_bf16_f32 v45, v74, v75
	ds_read2_b64 v[74:77], v82 offset1:4
	ds_read2_b64 v[78:81], v82 offset0:8 offset1:12
	s_waitcnt lgkmcnt(1)
	v_mfma_f32_16x16x32_bf16 v[74:77], v[50:53], v[74:77], 0
	s_waitcnt lgkmcnt(0)
	v_mfma_f32_16x16x32_bf16 v[74:77], v[54:57], v[78:81], v[74:77]
	ds_read2_b64 v[78:81], v82 offset0:16 offset1:20
	s_waitcnt lgkmcnt(0)
	v_mfma_f32_16x16x32_bf16 v[74:77], v[58:61], v[78:81], v[74:77]
	ds_read2_b64 v[78:81], v82 offset0:24 offset1:28
	s_waitcnt lgkmcnt(0)
	v_mfma_f32_16x16x32_bf16 v[74:77], v[62:65], v[78:81], v[74:77]
	ds_read_b128 v[78:81], v231 offset:53248
	ds_read_b128 v[82:85], v232
	s_waitcnt lgkmcnt(1)
	v_mfma_f32_16x16x32_bf16 v[74:77], v[66:69], v[78:81], v[74:77]
	s_waitcnt lgkmcnt(0)
	v_mfma_f32_16x16x32_bf16 v[74:77], v[46:49], v[82:85], v[74:77]
	ds_read_b128 v[78:81], v231 offset:53312
	ds_read_b128 v[82:85], v232 offset:64
	s_waitcnt lgkmcnt(1)
	v_mfma_f32_16x16x32_bf16 v[74:77], v[70:73], v[78:81], v[74:77]
	s_waitcnt lgkmcnt(0)
	v_mfma_f32_16x16x32_bf16 v[74:77], v[42:45], v[82:85], v[74:77]
	v_add_u32_e32 v78, 0x1100, v230
	v_add_u32_e32 v86, 0x4800, v78
	ds_read2_b64 v[78:81], v86 offset1:4
	ds_read2_b64 v[82:85], v86 offset0:8 offset1:12
	s_waitcnt lgkmcnt(1)
	v_mfma_f32_16x16x32_bf16 v[78:81], v[50:53], v[78:81], 0
	s_waitcnt lgkmcnt(0)
	v_mfma_f32_16x16x32_bf16 v[78:81], v[54:57], v[82:85], v[78:81]
	ds_read2_b64 v[82:85], v86 offset0:16 offset1:20
	s_waitcnt lgkmcnt(0)
	v_mfma_f32_16x16x32_bf16 v[78:81], v[58:61], v[82:85], v[78:81]
	ds_read2_b64 v[82:85], v86 offset0:24 offset1:28
	s_waitcnt lgkmcnt(0)
	v_mfma_f32_16x16x32_bf16 v[78:81], v[62:65], v[82:85], v[78:81]
	ds_read_b128 v[82:85], v231 offset:55552
	s_waitcnt lgkmcnt(0)
	v_mfma_f32_16x16x32_bf16 v[78:81], v[66:69], v[82:85], v[78:81]
	ds_read_b128 v[82:85], v233
	s_waitcnt lgkmcnt(0)
	v_mfma_f32_16x16x32_bf16 v[78:81], v[46:49], v[82:85], v[78:81]
	ds_read_b128 v[82:85], v231 offset:55616
	s_waitcnt lgkmcnt(0)
	v_mfma_f32_16x16x32_bf16 v[78:81], v[70:73], v[82:85], v[78:81]
	ds_read_b128 v[82:85], v233 offset:64
	s_waitcnt lgkmcnt(0)
	v_mfma_f32_16x16x32_bf16 v[78:81], v[42:45], v[82:85], v[78:81]
	v_add_u32_e32 v82, 0x2200, v230
	v_add_u32_e32 v90, 0x4800, v82
	ds_read2_b64 v[82:85], v90 offset1:4
	ds_read2_b64 v[86:89], v90 offset0:8 offset1:12
	s_waitcnt lgkmcnt(1)
	v_mfma_f32_16x16x32_bf16 v[82:85], v[50:53], v[82:85], 0
	s_waitcnt lgkmcnt(0)
	v_mfma_f32_16x16x32_bf16 v[82:85], v[54:57], v[86:89], v[82:85]
	ds_read2_b64 v[86:89], v90 offset0:16 offset1:20
	s_waitcnt lgkmcnt(0)
	v_mfma_f32_16x16x32_bf16 v[82:85], v[58:61], v[86:89], v[82:85]
	ds_read2_b64 v[86:89], v90 offset0:24 offset1:28
	s_waitcnt lgkmcnt(0)
	v_mfma_f32_16x16x32_bf16 v[82:85], v[62:65], v[86:89], v[82:85]
	ds_read_b128 v[86:89], v231 offset:57856
	s_waitcnt lgkmcnt(0)
	v_mfma_f32_16x16x32_bf16 v[82:85], v[66:69], v[86:89], v[82:85]
	ds_read_b128 v[86:89], v234
	s_waitcnt lgkmcnt(0)
	v_mfma_f32_16x16x32_bf16 v[82:85], v[46:49], v[86:89], v[82:85]
	ds_read_b128 v[86:89], v231 offset:57920
	s_waitcnt lgkmcnt(0)
	v_mfma_f32_16x16x32_bf16 v[82:85], v[70:73], v[86:89], v[82:85]
	ds_read_b128 v[86:89], v234 offset:64
	s_waitcnt lgkmcnt(0)
; #define LAS __attribute__((address_space(3)))
; __device__ __forceinline__ void ret_out_phase(const Args& A, Frame& F, int l, bool lastl, bf16_t* ARET, bf16_t* ALRU) {
;     ...
;         f32x4 O[8];
; #pragma unroll
;         for (int dvt = 0; dvt < 8; ++dvt) {
;             f32x4 o = (f32x4){0.f, 0.f, 0.f, 0.f};
; #pragma unroll
;             for (int jp = 0; jp < 4; ++jp) {
;                 const u32x2 lo = *(const LAS u32x2*)(vts + (16 * dvt + fr) * 136 + 32 * jp + 4 * fq);
;                 const u32x2 hi = *(const LAS u32x2*)(vts + (16 * dvt + fr) * 136 + 32 * jp + 16 + 4 * fq);
;                 u32x4 bv; bv[0] = lo.x; bv[1] = lo.y; bv[2] = hi.x; bv[3] = hi.y;
;                 o = __builtin_amdgcn_mfma_f32_16x16x32_bf16(pa[jp], __builtin_bit_cast(bf16x8, bv), o, 0, 0, 0);
;             }
; #pragma unroll
;             for (int ks = 0; ks < 2; ++ks) {
;                 const bf16x8 sf = *(const LAS bf16x8*)(sfs + (16 * dvt + fr) * 72 + 32 * ks + 8 * fq);
;                 const bf16x8 sb = *(const LAS bf16x8*)(sbs + (16 * dvt + fr) * 72 + 32 * ks + 8 * fq);
;                 o = __builtin_amdgcn_mfma_f32_16x16x32_bf16(qF[ks], sf, o, 0, 0, 0);
;                 o = __builtin_amdgcn_mfma_f32_16x16x32_bf16(qB[ks], sb, o, 0, 0, 0);
;             }
;             O[dvt] = o;
;             __builtin_amdgcn_sched_barrier(0);
;         }
	v_mfma_f32_16x16x32_bf16 v[82:85], v[42:45], v[86:89], v[82:85]
	v_add_u32_e32 v86, 0x3300, v230
	v_add_u32_e32 v94, 0x4800, v86
	ds_read2_b64 v[86:89], v94 offset1:4
	ds_read2_b64 v[90:93], v94 offset0:8 offset1:12
	s_waitcnt lgkmcnt(1)
	v_mfma_f32_16x16x32_bf16 v[86:89], v[50:53], v[86:89], 0
	s_waitcnt lgkmcnt(0)
	v_mfma_f32_16x16x32_bf16 v[86:89], v[54:57], v[90:93], v[86:89]
	ds_read2_b64 v[90:93], v94 offset0:16 offset1:20
	s_waitcnt lgkmcnt(0)
	v_mfma_f32_16x16x32_bf16 v[86:89], v[58:61], v[90:93], v[86:89]
	ds_read2_b64 v[90:93], v94 offset0:24 offset1:28
	s_waitcnt lgkmcnt(0)
	v_mfma_f32_16x16x32_bf16 v[86:89], v[62:65], v[90:93], v[86:89]
	ds_read_b128 v[90:93], v160 offset:55552
	s_waitcnt lgkmcnt(0)
	v_mfma_f32_16x16x32_bf16 v[86:89], v[66:69], v[90:93], v[86:89]
	ds_read_b128 v[90:93], v235
	s_waitcnt lgkmcnt(0)
	v_mfma_f32_16x16x32_bf16 v[86:89], v[46:49], v[90:93], v[86:89]
	ds_read_b128 v[90:93], v160 offset:55616
	s_waitcnt lgkmcnt(0)
	v_mfma_f32_16x16x32_bf16 v[86:89], v[70:73], v[90:93], v[86:89]
	ds_read_b128 v[90:93], v235 offset:64
	s_waitcnt lgkmcnt(0)
	v_mfma_f32_16x16x32_bf16 v[86:89], v[42:45], v[90:93], v[86:89]
	v_add_u32_e32 v90, 0x4400, v230
	v_add_u32_e32 v98, 0x4800, v90
	ds_read2_b64 v[90:93], v98 offset1:4
	ds_read2_b64 v[94:97], v98 offset0:8 offset1:12
	s_waitcnt lgkmcnt(1)
	v_mfma_f32_16x16x32_bf16 v[90:93], v[50:53], v[90:93], 0
	s_waitcnt lgkmcnt(0)
	v_mfma_f32_16x16x32_bf16 v[90:93], v[54:57], v[94:97], v[90:93]
	ds_read2_b64 v[94:97], v98 offset0:16 offset1:20
	s_waitcnt lgkmcnt(0)
	v_mfma_f32_16x16x32_bf16 v[90:93], v[58:61], v[94:97], v[90:93]
	ds_read2_b64 v[94:97], v98 offset0:24 offset1:28
	s_waitcnt lgkmcnt(0)
	v_mfma_f32_16x16x32_bf16 v[90:93], v[62:65], v[94:97], v[90:93]
	ds_read_b128 v[94:97], v236 offset:53248
	s_waitcnt lgkmcnt(0)
	v_mfma_f32_16x16x32_bf16 v[90:93], v[66:69], v[94:97], v[90:93]
	ds_read_b128 v[94:97], v237
	s_waitcnt lgkmcnt(0)
	v_mfma_f32_16x16x32_bf16 v[90:93], v[46:49], v[94:97], v[90:93]
	ds_read_b128 v[94:97], v236 offset:53312
	s_waitcnt lgkmcnt(0)
	v_mfma_f32_16x16x32_bf16 v[90:93], v[70:73], v[94:97], v[90:93]
	ds_read_b128 v[94:97], v237 offset:64
	s_waitcnt lgkmcnt(0)
	v_mfma_f32_16x16x32_bf16 v[90:93], v[42:45], v[94:97], v[90:93]
	v_add_u32_e32 v94, 0x5500, v230
	v_add_u32_e32 v129, 0x4800, v94
	ds_read2_b64 v[94:97], v129 offset1:4
	ds_read2_b64 v[98:101], v129 offset0:8 offset1:12
	s_waitcnt lgkmcnt(1)
	v_mfma_f32_16x16x32_bf16 v[94:97], v[50:53], v[94:97], 0
	s_waitcnt lgkmcnt(0)
	v_mfma_f32_16x16x32_bf16 v[94:97], v[54:57], v[98:101], v[94:97]
	ds_read2_b64 v[98:101], v129 offset0:16 offset1:20
	s_waitcnt lgkmcnt(0)
	v_mfma_f32_16x16x32_bf16 v[94:97], v[58:61], v[98:101], v[94:97]
	ds_read2_b64 v[98:101], v129 offset0:24 offset1:28
	s_waitcnt lgkmcnt(0)
	v_mfma_f32_16x16x32_bf16 v[94:97], v[62:65], v[98:101], v[94:97]
	ds_read_b128 v[98:101], v238 offset:53248
	s_waitcnt lgkmcnt(0)
	v_mfma_f32_16x16x32_bf16 v[94:97], v[66:69], v[98:101], v[94:97]
	ds_read_b128 v[98:101], v239
	s_waitcnt lgkmcnt(0)
	v_mfma_f32_16x16x32_bf16 v[94:97], v[46:49], v[98:101], v[94:97]
	ds_read_b128 v[98:101], v238 offset:53312
	s_waitcnt lgkmcnt(0)
	v_mfma_f32_16x16x32_bf16 v[94:97], v[70:73], v[98:101], v[94:97]
	ds_read_b128 v[98:101], v239 offset:64
	s_waitcnt lgkmcnt(0)
	v_mfma_f32_16x16x32_bf16 v[94:97], v[42:45], v[98:101], v[94:97]
	v_add_u32_e32 v98, 0x6600, v230
	v_add_u32_e32 v129, 0x4800, v98
	ds_read2_b64 v[98:101], v129 offset1:4
	ds_read2_b64 v[250:253], v129 offset0:8 offset1:12
	s_waitcnt lgkmcnt(1)
	v_mfma_f32_16x16x32_bf16 v[98:101], v[50:53], v[98:101], 0
	s_waitcnt lgkmcnt(0)
	v_mfma_f32_16x16x32_bf16 v[98:101], v[54:57], v[250:253], v[98:101]
	ds_read2_b64 v[250:253], v129 offset0:16 offset1:20
	s_waitcnt lgkmcnt(0)
	v_mfma_f32_16x16x32_bf16 v[98:101], v[58:61], v[250:253], v[98:101]
	ds_read2_b64 v[250:253], v129 offset0:24 offset1:28
	s_waitcnt lgkmcnt(0)
	v_mfma_f32_16x16x32_bf16 v[98:101], v[62:65], v[250:253], v[98:101]
	ds_read_b128 v[250:253], v240 offset:53248
	s_waitcnt lgkmcnt(0)
	v_mfma_f32_16x16x32_bf16 v[98:101], v[66:69], v[250:253], v[98:101]
	ds_read_b128 v[250:253], v241
	s_waitcnt lgkmcnt(0)
	v_mfma_f32_16x16x32_bf16 v[98:101], v[46:49], v[250:253], v[98:101]
	ds_read_b128 v[250:253], v240 offset:53312
	s_waitcnt lgkmcnt(0)
	v_mfma_f32_16x16x32_bf16 v[98:101], v[70:73], v[250:253], v[98:101]
	ds_read_b128 v[250:253], v241 offset:64
	s_waitcnt lgkmcnt(0)
	v_mfma_f32_16x16x32_bf16 v[98:101], v[42:45], v[250:253], v[98:101]
	v_add_u32_e32 v129, 0x4800, v242
	ds_read2_b64 v[250:253], v129 offset1:4
	s_waitcnt lgkmcnt(0)
	v_mfma_f32_16x16x32_bf16 v[50:53], v[50:53], v[250:253], 0
	ds_read2_b64 v[250:253], v129 offset0:8 offset1:12
	s_waitcnt lgkmcnt(0)
	v_mfma_f32_16x16x32_bf16 v[50:53], v[54:57], v[250:253], v[50:53]
	ds_read2_b64 v[54:57], v129 offset0:16 offset1:20
	s_waitcnt lgkmcnt(0)
	v_mfma_f32_16x16x32_bf16 v[50:53], v[58:61], v[54:57], v[50:53]
	ds_read2_b64 v[54:57], v129 offset0:24 offset1:28
	s_waitcnt lgkmcnt(0)
	v_mfma_f32_16x16x32_bf16 v[50:53], v[62:65], v[54:57], v[50:53]
	ds_read_b128 v[54:57], v243 offset:53248
	ds_read_b128 v[58:61], v243 offset:53312
	s_waitcnt lgkmcnt(1)
	v_mfma_f32_16x16x32_bf16 v[50:53], v[66:69], v[54:57], v[50:53]
	ds_read_b128 v[54:57], v244
	ds_read_b128 v[62:65], v244 offset:64
	s_waitcnt lgkmcnt(1)
	v_mfma_f32_16x16x32_bf16 v[46:49], v[46:49], v[54:57], v[50:53]
	v_mfma_f32_16x16x32_bf16 v[46:49], v[70:73], v[58:61], v[46:49]
	s_waitcnt lgkmcnt(0)
; __device__ __forceinline__ bf16_t f2bf(float f) { return (bf16_t)(pk2(f, 0.f) & 0xffffu); }
; __device__ __forceinline__ void ret_out_phase(const Args& A, Frame& F, int l, bool lastl, bf16_t* ARET, bf16_t* ALRU) {
;     ...
; #pragma unroll
;         for (int r = 0; r < 4; ++r) {
;             float sm = 0.f;
; #pragma unroll
;             for (int dvt = 0; dvt < 8; ++dvt) sm += O[dvt][r];
;             const float mu = sum16(sm) * (1.f / DV);
;             float q2 = 0.f;
; #pragma unroll
;             for (int dvt = 0; dvt < 8; ++dvt) { const float dd = O[dvt][r] - mu; q2 += dd * dd; }
;             const float rstd = rsqrtf(sum16(q2) * (1.f / DV) + EPS);
; #pragma unroll
;             for (int dvt = 0; dvt < 8; ++dvt) os[(16 * w + 4 * fq + r) * 136 + 16 * dvt + fr] = f2bf((O[dvt][r] - mu) * rstd);
;         }
	v_mfma_f32_16x16x32_bf16 v[42:45], v[42:45], v[62:65], v[46:49]
	s_nop 5
	v_add_f32_e64 v46, v74, 0
	v_add_f32_e64 v47, v75, 0
	v_mov_b32_e32 v50, v86
	v_pk_add_f32 v[46:47], v[46:47], v[78:79]
	v_mov_b32_e32 v51, v82
	v_pk_add_f32 v[46:47], v[46:47], v[82:83]
	v_mov_b32_e32 v82, v87
	v_pk_add_f32 v[46:47], v[46:47], v[86:87]
	v_mov_b32_e32 v52, v94
	v_pk_add_f32 v[46:47], v[46:47], v[90:91]
	v_mov_b32_e32 v53, v90
	v_pk_add_f32 v[46:47], v[46:47], v[94:95]
	v_mov_b32_e32 v90, v95
	v_pk_add_f32 v[46:47], v[46:47], v[98:99]
	v_mov_b32_e32 v54, v42
	v_pk_add_f32 v[46:47], v[46:47], v[42:43]
	v_mov_b32_e32 v55, v98
	v_mov_b32_e32 v98, v43
	s_mov_b32 s2, 0x358637bd
	s_add_i32 vcc_hi, vcc_hi, s34
	s_waitcnt lgkmcnt(0)
	s_nop 1
	v_add_f32_dpp v46, v46, v46 quad_perm:[1,0,3,2] row_mask:0xf bank_mask:0xf
	v_add_f32_dpp v47, v47, v47 quad_perm:[1,0,3,2] row_mask:0xf bank_mask:0xf
	s_add_i32 s61, s61, s60
	s_cmp_lg_u32 s37, s39
	s_waitcnt lgkmcnt(0)
	s_nop 1
	v_add_f32_dpp v46, v46, v46 quad_perm:[2,3,0,1] row_mask:0xf bank_mask:0xf
	v_add_f32_dpp v47, v47, v47 quad_perm:[2,3,0,1] row_mask:0xf bank_mask:0xf
	s_waitcnt lgkmcnt(0)
	s_nop 1
	v_add_f32_dpp v46, v46, v46 row_half_mirror row_mask:0xf bank_mask:0xf
	v_add_f32_dpp v47, v47, v47 row_half_mirror row_mask:0xf bank_mask:0xf
	s_waitcnt lgkmcnt(0)
	s_nop 1
	v_add_f32_dpp v46, v46, v46 row_mirror row_mask:0xf bank_mask:0xf
	v_add_f32_dpp v47, v47, v47 row_mirror row_mask:0xf bank_mask:0xf
	s_nop 0
	v_pk_mul_f32 v[48:49], v[46:47], s[18:19] op_sel_hi:[1,0]
	v_pk_fma_f32 v[64:65], v[46:47], s[18:19], v[78:79] op_sel_hi:[1,0,1] neg_lo:[1,0,0] neg_hi:[1,0,0]
	v_pk_add_f32 v[50:51], v[50:51], v[48:49] op_sel_hi:[1,0] neg_lo:[0,1] neg_hi:[0,1]
	v_pk_add_f32 v[68:69], v[82:83], v[48:49] op_sel:[0,1] neg_lo:[0,1] neg_hi:[0,1]
	v_pk_fma_f32 v[56:57], v[46:47], s[18:19], v[74:75] op_sel_hi:[1,0,1] neg_lo:[1,0,0] neg_hi:[1,0,0]
	v_pk_mul_f32 v[58:59], v[50:51], v[50:51]
	v_pk_mul_f32 v[46:47], v[64:65], v[64:65]
	v_pk_mul_f32 v[70:71], v[68:69], v[68:69]
	v_pk_add_f32 v[52:53], v[52:53], v[48:49] op_sel_hi:[1,0] neg_lo:[0,1] neg_hi:[0,1]
	v_pk_fma_f32 v[66:67], v[56:57], v[56:57], v[46:47]
	v_pk_add_f32 v[46:47], v[90:91], v[48:49] op_sel:[0,1] neg_lo:[0,1] neg_hi:[0,1]
	v_mov_b32_e32 v75, v58
	v_mov_b32_e32 v58, v71
	v_pk_mul_f32 v[60:61], v[52:53], v[52:53]
	v_pk_mul_f32 v[72:73], v[46:47], v[46:47]
	v_mov_b32_e32 v74, v70
	v_pk_add_f32 v[58:59], v[58:59], v[66:67] op_sel:[0,1] op_sel_hi:[1,0]
	v_pk_add_f32 v[54:55], v[54:55], v[48:49] op_sel_hi:[1,0] neg_lo:[0,1] neg_hi:[0,1]
	v_pk_add_f32 v[42:43], v[98:99], v[48:49] op_sel:[0,1] neg_lo:[0,1] neg_hi:[0,1]
	v_pk_add_f32 v[58:59], v[74:75], v[58:59]
	v_mov_b32_e32 v66, v73
	v_mov_b32_e32 v67, v61
	v_pk_mul_f32 v[62:63], v[54:55], v[54:55]
	v_pk_mul_f32 v[48:49], v[42:43], v[42:43]
	v_pk_add_f32 v[58:59], v[66:67], v[58:59]
	v_mov_b32_e32 v73, v60
	v_pk_add_f32 v[58:59], v[72:73], v[58:59]
	v_mov_b32_e32 v60, v49
	v_mov_b32_e32 v61, v63
	v_pk_add_f32 v[58:59], v[60:61], v[58:59]
	v_mov_b32_e32 v49, v62
	v_pk_add_f32 v[48:49], v[48:49], v[58:59]
	s_waitcnt lgkmcnt(0)
	s_nop 1
	v_add_f32_dpp v48, v48, v48 quad_perm:[1,0,3,2] row_mask:0xf bank_mask:0xf
	v_add_f32_dpp v49, v49, v49 quad_perm:[1,0,3,2] row_mask:0xf bank_mask:0xf
	s_waitcnt lgkmcnt(0)
	s_nop 1
	v_add_f32_dpp v48, v48, v48 quad_perm:[2,3,0,1] row_mask:0xf bank_mask:0xf
	v_add_f32_dpp v49, v49, v49 quad_perm:[2,3,0,1] row_mask:0xf bank_mask:0xf
	s_waitcnt lgkmcnt(0)
	s_nop 1
	v_add_f32_dpp v48, v48, v48 row_half_mirror row_mask:0xf bank_mask:0xf
	v_add_f32_dpp v49, v49, v49 row_half_mirror row_mask:0xf bank_mask:0xf
	s_waitcnt lgkmcnt(0)
	s_nop 1
	v_add_f32_dpp v48, v48, v48 row_mirror row_mask:0xf bank_mask:0xf
	v_add_f32_dpp v49, v49, v49 row_mirror row_mask:0xf bank_mask:0xf
	v_mov_b64_e32 v[58:59], s[2:3]
	v_pk_fma_f32 v[48:49], v[48:49], s[18:19], v[58:59] op_sel_hi:[1,0,0]
	s_mov_b32 s2, 0xfcc8000
	v_mul_f32_e32 v60, 0x4b800000, v49
	v_cmp_gt_f32_e64 s[74:75], s33, v49
	s_nop 1
	v_cndmask_b32_e64 v49, v49, v60, s[74:75]
	v_rsq_f32_e32 v49, v49
	s_nop 0
	v_mul_f32_e32 v60, 0x45800000, v49
	v_cndmask_b32_e64 v49, v49, v60, s[74:75]
	v_mul_f32_e32 v50, v50, v49
	v_cvt_pk_bf16_f32 v50, v50, s0
	ds_write_b16 v249, v50 offset:96
	v_mul_f32_e32 v50, v53, v49
	v_cvt_pk_bf16_f32 v50, v50, s0
	v_mul_f32_e32 v56, v56, v49
	ds_write_b16 v249, v50 offset:128
	v_mul_f32_e32 v50, v52, v49
	v_cvt_pk_bf16_f32 v56, v56, s0
	v_cvt_pk_bf16_f32 v50, v50, s0
	ds_write_b16 v249, v56
	v_mul_f32_e32 v56, v64, v49
	v_mul_f32_e32 v51, v51, v49
	ds_write_b16 v249, v50 offset:160
	v_mul_f32_e32 v50, v55, v49
	v_mul_f32_e32 v52, v54, v49
	v_mul_f32_e32 v49, 0x4b800000, v48
	v_cmp_gt_f32_e64 s[74:75], s33, v48
	v_cvt_pk_bf16_f32 v51, v51, s0
	v_cvt_pk_bf16_f32 v50, v50, s0
	v_cndmask_b32_e64 v48, v48, v49, s[74:75]
	v_rsq_f32_e32 v53, v48
	v_pk_add_f32 v[48:49], v[76:77], 0 op_sel_hi:[1,0]
	ds_write_b16 v249, v51 offset:64
	v_pk_add_f32 v[48:49], v[48:49], v[80:81]
	ds_write_b16 v249, v50 offset:192
	v_pk_add_f32 v[48:49], v[48:49], v[84:85]
	v_cvt_pk_bf16_f32 v52, v52, s0
	v_pk_add_f32 v[48:49], v[48:49], v[88:89]
	ds_write_b16 v249, v52 offset:224
	v_pk_add_f32 v[48:49], v[48:49], v[92:93]
	v_mul_f32_e32 v52, 0x45800000, v53
	v_pk_add_f32 v[48:49], v[48:49], v[96:97]
	v_cndmask_b32_e64 v82, v53, v52, s[74:75]
	v_pk_add_f32 v[48:49], v[48:49], v[100:101]
	v_mul_f32_e32 v52, v57, v82
	v_pk_add_f32 v[48:49], v[48:49], v[44:45]
	v_cvt_pk_bf16_f32 v52, v52, s0
	ds_write_b16 v249, v52 offset:272
	v_mul_f32_e32 v52, v65, v82
	v_cvt_pk_bf16_f32 v83, v52, s0
	s_waitcnt lgkmcnt(1)
; #define LAS __attribute__((address_space(3)))
; __device__ __forceinline__ bf16_t f2bf(float f) { return (bf16_t)(pk2(f, 0.f) & 0xffffu); }
; __device__ __forceinline__ void ret_out_phase(const Args& A, Frame& F, int l, bool lastl, bf16_t* ARET, bf16_t* ALRU) {
;     ...
; #pragma unroll
;         for (int r = 0; r < 4; ++r) {
;             float sm = 0.f;
; #pragma unroll
;             for (int dvt = 0; dvt < 8; ++dvt) sm += O[dvt][r];
;             const float mu = sum16(sm) * (1.f / DV);
;             float q2 = 0.f;
; #pragma unroll
;             for (int dvt = 0; dvt < 8; ++dvt) { const float dd = O[dvt][r] - mu; q2 += dd * dd; }
;             const float rstd = rsqrtf(sum16(q2) * (1.f / DV) + EPS);
; #pragma unroll
;             for (int dvt = 0; dvt < 8; ++dvt) os[(16 * w + 4 * fq + r) * 136 + 16 * dvt + fr] = f2bf((O[dvt][r] - mu) * rstd);
;         }
;         __builtin_amdgcn_fence(__ATOMIC_RELEASE, "workgroup"); __builtin_amdgcn_wave_barrier(); __builtin_amdgcn_fence(__ATOMIC_ACQUIRE, "workgroup");
;         {
;             const int rr = 16 * w + (lane >> 2), cc = (lane & 3) * 32;
;             const size_t go = (rowbase + rr) * D + 128 * h + cc;
; #pragma unroll
;             for (int i = 0; i < 4; ++i) {
;                 const u32x4 ov = *(const LAS u32x4*)(os + rr * 136 + cc + 8 * i);
;                 const u32x4 gv = *(const u32x4*)(WSB(WS_SG) + go + 8 * i);
	s_nop 1
	v_add_f32_dpp v48, v48, v48 quad_perm:[1,0,3,2] row_mask:0xf bank_mask:0xf
	v_add_f32_dpp v49, v49, v49 quad_perm:[1,0,3,2] row_mask:0xf bank_mask:0xf
	v_mov_b32_e32 v52, v88
	v_mov_b32_e32 v53, v84
	v_mov_b32_e32 v84, v89
	v_mov_b32_e32 v54, v96
	s_waitcnt lgkmcnt(0)
	s_nop 1
	v_add_f32_dpp v48, v48, v48 quad_perm:[2,3,0,1] row_mask:0xf bank_mask:0xf
	v_add_f32_dpp v49, v49, v49 quad_perm:[2,3,0,1] row_mask:0xf bank_mask:0xf
	v_mov_b32_e32 v55, v92
	v_mov_b32_e32 v92, v97
	v_cvt_pk_bf16_f32 v56, v56, s0
	ds_write_b16 v249, v56 offset:32
	s_waitcnt lgkmcnt(1)
	s_nop 1
	v_add_f32_dpp v48, v48, v48 row_half_mirror row_mask:0xf bank_mask:0xf
	v_add_f32_dpp v49, v49, v49 row_half_mirror row_mask:0xf bank_mask:0xf
	v_mov_b32_e32 v56, v44
	v_mov_b32_e32 v57, v100
	v_mov_b32_e32 v100, v45
	v_mul_f32_e32 v47, v47, v82
	s_waitcnt lgkmcnt(0)
	s_nop 1
	v_add_f32_dpp v48, v48, v48 row_mirror row_mask:0xf bank_mask:0xf
	v_add_f32_dpp v49, v49, v49 row_mirror row_mask:0xf bank_mask:0xf
	v_cvt_pk_bf16_f32 v47, v47, s0
	v_pk_mul_f32 v[50:51], v[48:49], s[18:19] op_sel_hi:[1,0]
	v_pk_fma_f32 v[66:67], v[48:49], s[18:19], v[76:77] op_sel_hi:[1,0,1] neg_lo:[1,0,0] neg_hi:[1,0,0]
	v_pk_add_f32 v[52:53], v[52:53], v[50:51] op_sel_hi:[1,0] neg_lo:[0,1] neg_hi:[0,1]
	v_pk_fma_f32 v[48:49], v[48:49], s[18:19], v[80:81] op_sel_hi:[1,0,1] neg_lo:[1,0,0] neg_hi:[1,0,0]
	v_pk_add_f32 v[72:73], v[84:85], v[50:51] op_sel:[0,1] neg_lo:[0,1] neg_hi:[0,1]
	v_pk_mul_f32 v[60:61], v[52:53], v[52:53]
	v_pk_mul_f32 v[70:71], v[48:49], v[48:49]
	v_pk_mul_f32 v[74:75], v[72:73], v[72:73]
	v_pk_add_f32 v[54:55], v[54:55], v[50:51] op_sel_hi:[1,0] neg_lo:[0,1] neg_hi:[0,1]
	v_pk_fma_f32 v[70:71], v[66:67], v[66:67], v[70:71]
	v_pk_add_f32 v[76:77], v[92:93], v[50:51] op_sel:[0,1] neg_lo:[0,1] neg_hi:[0,1]
	v_mov_b32_e32 v81, v60
	v_mov_b32_e32 v60, v75
	v_pk_mul_f32 v[62:63], v[54:55], v[54:55]
	v_pk_mul_f32 v[78:79], v[76:77], v[76:77]
	v_mov_b32_e32 v80, v74
	v_pk_add_f32 v[60:61], v[60:61], v[70:71] op_sel:[0,1] op_sel_hi:[1,0]
	v_pk_add_f32 v[56:57], v[56:57], v[50:51] op_sel_hi:[1,0] neg_lo:[0,1] neg_hi:[0,1]
	v_pk_add_f32 v[44:45], v[100:101], v[50:51] op_sel:[0,1] neg_lo:[0,1] neg_hi:[0,1]
	v_pk_add_f32 v[60:61], v[80:81], v[60:61]
	v_mov_b32_e32 v70, v79
	v_mov_b32_e32 v71, v63
	v_pk_mul_f32 v[64:65], v[56:57], v[56:57]
	v_pk_mul_f32 v[50:51], v[44:45], v[44:45]
	v_pk_add_f32 v[60:61], v[70:71], v[60:61]
	v_mov_b32_e32 v79, v62
	v_pk_add_f32 v[60:61], v[78:79], v[60:61]
	v_mov_b32_e32 v62, v51
	v_mov_b32_e32 v63, v65
	v_pk_add_f32 v[60:61], v[62:63], v[60:61]
	v_mov_b32_e32 v51, v64
	v_pk_add_f32 v[50:51], v[50:51], v[60:61]
	v_mul_f32_e32 v62, v69, v82
	v_cvt_pk_bf16_f32 v62, v62, s0
	ds_write_b16 v249, v62 offset:336
	v_mul_f32_e32 v62, v68, v82
	s_waitcnt lgkmcnt(1)
	s_nop 1
	v_add_f32_dpp v50, v50, v50 quad_perm:[1,0,3,2] row_mask:0xf bank_mask:0xf
	v_add_f32_dpp v51, v51, v51 quad_perm:[1,0,3,2] row_mask:0xf bank_mask:0xf
	v_cvt_pk_bf16_f32 v62, v62, s0
	v_mul_f32_e32 v46, v46, v82
	ds_write_b16 v249, v62 offset:368
	ds_write_b16 v249, v47 offset:400
	s_waitcnt lgkmcnt(2)
	s_nop 1
	v_add_f32_dpp v50, v50, v50 quad_perm:[2,3,0,1] row_mask:0xf bank_mask:0xf
	v_add_f32_dpp v51, v51, v51 quad_perm:[2,3,0,1] row_mask:0xf bank_mask:0xf
	v_cvt_pk_bf16_f32 v62, v46, s0
	v_mul_f32_e32 v43, v43, v82
	v_cvt_pk_bf16_f32 v43, v43, s0
	ds_write_b16 v249, v43 offset:464
	s_waitcnt lgkmcnt(1)
	s_nop 1
	v_add_f32_dpp v46, v50, v50 row_half_mirror row_mask:0xf bank_mask:0xf
	v_add_f32_dpp v47, v51, v51 row_half_mirror row_mask:0xf bank_mask:0xf
	v_mul_f32_e32 v42, v42, v82
	v_cvt_pk_bf16_f32 v42, v42, s0
	ds_write_b16 v249, v42 offset:496
	ds_write_b16 v249, v83 offset:304
	s_waitcnt lgkmcnt(2)
	s_nop 1
	v_add_f32_dpp v46, v46, v46 row_mirror row_mask:0xf bank_mask:0xf
	v_add_f32_dpp v47, v47, v47 row_mirror row_mask:0xf bank_mask:0xf
	ds_write_b16 v249, v62 offset:432
	v_pk_fma_f32 v[46:47], v[46:47], s[18:19], v[58:59] op_sel_hi:[1,0,0]
	s_nop 0
	v_mul_f32_e32 v43, 0x4b800000, v47
	v_cmp_gt_f32_e64 s[74:75], s33, v47
	s_nop 1
	v_cndmask_b32_e64 v43, v47, v43, s[74:75]
	v_rsq_f32_e32 v43, v43
	s_nop 0
	v_mul_f32_e32 v42, 0x45800000, v43
	v_cndmask_b32_e64 v42, v43, v42, s[74:75]
	v_mul_f32_e32 v43, v66, v42
	v_cvt_pk_bf16_f32 v43, v43, s0
	ds_write_b16 v249, v43 offset:544
	v_mul_f32_e32 v43, v48, v42
	v_cvt_pk_bf16_f32 v43, v43, s0
	ds_write_b16 v249, v43 offset:576
	v_mul_f32_e32 v43, v53, v42
	v_cvt_pk_bf16_f32 v43, v43, s0
	ds_write_b16 v249, v43 offset:608
	v_mul_f32_e32 v43, v52, v42
	v_cvt_pk_bf16_f32 v43, v43, s0
	ds_write_b16 v249, v43 offset:640
	v_mul_f32_e32 v43, v55, v42
	v_cvt_pk_bf16_f32 v43, v43, s0
	ds_write_b16 v249, v43 offset:672
	v_mul_f32_e32 v43, v54, v42
	v_cvt_pk_bf16_f32 v43, v43, s0
	ds_write_b16 v249, v43 offset:704
	v_mul_f32_e32 v43, v57, v42
	v_cvt_pk_bf16_f32 v43, v43, s0
	ds_write_b16 v249, v43 offset:736
	v_mul_f32_e32 v43, 0x4b800000, v46
	v_cmp_gt_f32_e64 s[74:75], s33, v46
	v_mul_f32_e32 v42, v56, v42
	v_cvt_pk_bf16_f32 v42, v42, s0
	v_cndmask_b32_e64 v43, v46, v43, s[74:75]
	v_rsq_f32_e32 v43, v43
	ds_write_b16 v249, v42 offset:768
	v_mul_f32_e32 v42, 0x45800000, v43
	v_cndmask_b32_e64 v42, v43, v42, s[74:75]
	v_mul_f32_e32 v43, v67, v42
	v_cvt_pk_bf16_f32 v43, v43, s0
	ds_write_b16 v249, v43 offset:816
	v_mul_f32_e32 v43, v49, v42
	v_cvt_pk_bf16_f32 v43, v43, s0
	ds_write_b16 v249, v43 offset:848
	v_mul_f32_e32 v43, v73, v42
	v_cvt_pk_bf16_f32 v43, v43, s0
	ds_write_b16 v249, v43 offset:880
	v_mul_f32_e32 v43, v72, v42
	v_cvt_pk_bf16_f32 v43, v43, s0
	ds_write_b16 v249, v43 offset:912
	v_mul_f32_e32 v43, v77, v42
	v_cvt_pk_bf16_f32 v43, v43, s0
	ds_write_b16 v249, v43 offset:944
	v_mul_f32_e32 v43, v76, v42
	v_cvt_pk_bf16_f32 v43, v43, s0
	ds_write_b16 v249, v43 offset:976
	v_mul_f32_e32 v43, v45, v42
	v_mul_f32_e32 v42, v44, v42
	v_cvt_pk_bf16_f32 v43, v43, s0
	v_cvt_pk_bf16_f32 v42, v42, s0
	ds_write_b16 v249, v43 offset:1008
	ds_write_b16 v249, v42 offset:1040
	v_lshl_add_u64 v[42:43], s[8:9], 0, v[124:125]
	v_lshlrev_b64 v[42:43], 10, v[42:43]
	v_or_b32_e32 v42, v42, v126
	v_or_b32_e32 v42, s82, v42
	v_lshlrev_b64 v[54:55], 1, v[42:43]
	v_lshl_add_u64 v[42:43], s[50:51], 0, v[54:55]
	s_waitcnt lgkmcnt(0)
; #define LAS __attribute__((address_space(3)))
; __device__ __forceinline__ unsigned pk2(float lo, float hi) { const f32x2_t v = {lo, hi}; const bf16v2_t b = __builtin_convertvector(v, bf16v2_t); return __builtin_bit_cast(unsigned, b); }
; __device__ __forceinline__ float bflo(unsigned u) { return __uint_as_float(u << 16); }
; __device__ __forceinline__ float bfhi(unsigned u) { return __uint_as_float(u & 0xffff0000u); }
; __device__ __forceinline__ void ret_out_phase(const Args& A, Frame& F, int l, bool lastl, bf16_t* ARET, bf16_t* ALRU) {
;     ...
;         {
;             const int rr = 16 * w + (lane >> 2), cc = (lane & 3) * 32;
;             const size_t go = (rowbase + rr) * D + 128 * h + cc;
; #pragma unroll
;             for (int i = 0; i < 4; ++i) {
;                 const u32x4 ov = *(const LAS u32x4*)(os + rr * 136 + cc + 8 * i);
;                 const u32x4 gv = *(const u32x4*)(WSB(WS_SG) + go + 8 * i);
;                 u32x4 rv;
; #pragma unroll
;                 for (int e = 0; e < 4; ++e) rv[e] = pk2(bflo(ov[e]) * bflo(gv[e]), bfhi(ov[e]) * bfhi(gv[e]));
;                 *(u32x4*)(ARET + go + 8 * i) = rv;
;             }
;         }
; #pragma unroll
;         for (int i = 0; i < 4; ++i) {
;             const int u = tid + i * NTHREADS, r = u >> 4, c8 = (u & 15) * 8;
;             const size_t o = (rowbase + r) * D + 128 * h + c8;
;             const u32x4 hf = *(const u32x4*)(WSB(WS_HF) + o), hb = *(const u32x4*)(WSB(WS_HB) + o), gg = *(const u32x4*)(WSB(WS_GG) + o);
;             u32x4 ov;
; #pragma unroll
;             for (int e = 0; e < 4; ++e) ov[e] = pk2((bflo(hf[e]) + bflo(hb[e])) * bflo(gg[e]), (bfhi(hf[e]) + bfhi(hb[e])) * bfhi(gg[e]));
;             *(u32x4*)(ALRU + o) = ov;
;         }
	v_add_u32_e32 v129, s8, v124
	v_lshlrev_b32_e32 v129, 11, v129
	v_or_b32_e32 v100, s82, v126
	v_lshl_or_b32 v129, v100, 1, v129
	v_or_b32_e32 v100, s82, v104
	v_add_u32_e32 v141, s8, v106
	v_lshlrev_b32_e32 v141, 11, v141
	v_lshl_or_b32 v141, v100, 1, v141
	v_add_u32_e32 v250, s8, v108
	v_lshlrev_b32_e32 v250, 11, v250
	v_lshl_or_b32 v250, v100, 1, v250
	v_add_u32_e32 v251, s8, v110
	v_lshlrev_b32_e32 v251, 11, v251
	v_lshl_or_b32 v251, v100, 1, v251
	v_add_u32_e32 v252, s8, v112
	v_lshlrev_b32_e32 v252, 11, v252
	v_lshl_or_b32 v252, v100, 1, v252
	global_load_dwordx4 v[56:59], v129, s[50:51]
	global_load_dwordx4 v[60:63], v129, s[50:51] offset:16
	global_load_dwordx4 v[64:67], v129, s[50:51] offset:32
	global_load_dwordx4 v[68:71], v129, s[50:51] offset:48
	global_load_dwordx4 v[72:75], v141, s[10:11]
	global_load_dwordx4 v[76:79], v141, s[12:13]
	global_load_dwordx4 v[80:83], v141, s[14:15]
	global_load_dwordx4 v[84:87], v250, s[10:11]
	global_load_dwordx4 v[88:91], v250, s[12:13]
	global_load_dwordx4 v[92:95], v250, s[14:15]
	ds_read_b128 v[96:99], v133
	ds_read_b128 v[44:47], v133 offset:16
	s_waitcnt vmcnt(9) lgkmcnt(1)
	v_lshlrev_b32_e32 v100, 16, v96
	v_and_b32_e32 v101, 0xffff0000, v96
	v_lshlrev_b32_e32 v52, 16, v56
	v_and_b32_e32 v53, 0xffff0000, v56
	v_pk_mul_f32 v[100:101], v[100:101], v[52:53]
	s_nop 0
	v_cvt_pk_bf16_f32 v56, v100, v101
	v_lshlrev_b32_e32 v100, 16, v97
	v_and_b32_e32 v101, 0xffff0000, v97
	v_lshlrev_b32_e32 v52, 16, v57
	v_and_b32_e32 v53, 0xffff0000, v57
	v_pk_mul_f32 v[100:101], v[100:101], v[52:53]
	s_nop 0
	v_cvt_pk_bf16_f32 v57, v100, v101
	v_lshlrev_b32_e32 v100, 16, v98
	v_and_b32_e32 v101, 0xffff0000, v98
	v_lshlrev_b32_e32 v52, 16, v58
	v_and_b32_e32 v53, 0xffff0000, v58
	v_pk_mul_f32 v[100:101], v[100:101], v[52:53]
	s_nop 0
	v_cvt_pk_bf16_f32 v58, v100, v101
	v_lshlrev_b32_e32 v100, 16, v99
	v_and_b32_e32 v101, 0xffff0000, v99
	v_lshlrev_b32_e32 v52, 16, v59
	v_and_b32_e32 v53, 0xffff0000, v59
	v_pk_mul_f32 v[100:101], v[100:101], v[52:53]
	s_nop 0
	v_cvt_pk_bf16_f32 v59, v100, v101
	global_store_dwordx4 v129, v[56:59], s[88:89]
	s_waitcnt vmcnt(9) lgkmcnt(0)
	v_lshlrev_b32_e32 v100, 16, v44
	v_and_b32_e32 v101, 0xffff0000, v44
	v_lshlrev_b32_e32 v52, 16, v60
	v_and_b32_e32 v53, 0xffff0000, v60
	v_pk_mul_f32 v[100:101], v[100:101], v[52:53]
	s_nop 0
	v_cvt_pk_bf16_f32 v60, v100, v101
	v_lshlrev_b32_e32 v100, 16, v45
	v_and_b32_e32 v101, 0xffff0000, v45
	v_lshlrev_b32_e32 v52, 16, v61
	v_and_b32_e32 v53, 0xffff0000, v61
	v_pk_mul_f32 v[100:101], v[100:101], v[52:53]
	s_nop 0
	v_cvt_pk_bf16_f32 v61, v100, v101
	v_lshlrev_b32_e32 v100, 16, v46
	v_and_b32_e32 v101, 0xffff0000, v46
	v_lshlrev_b32_e32 v52, 16, v62
	v_and_b32_e32 v53, 0xffff0000, v62
	v_pk_mul_f32 v[100:101], v[100:101], v[52:53]
	s_nop 0
	v_cvt_pk_bf16_f32 v62, v100, v101
	v_lshlrev_b32_e32 v100, 16, v47
	v_and_b32_e32 v101, 0xffff0000, v47
	v_lshlrev_b32_e32 v52, 16, v63
	v_and_b32_e32 v53, 0xffff0000, v63
	v_pk_mul_f32 v[100:101], v[100:101], v[52:53]
	s_nop 0
	v_cvt_pk_bf16_f32 v63, v100, v101
	global_store_dwordx4 v129, v[60:63], s[88:89] offset:16
	ds_read_b128 v[96:99], v133 offset:32
	ds_read_b128 v[44:47], v133 offset:48
	s_waitcnt vmcnt(9) lgkmcnt(1)
	v_lshlrev_b32_e32 v100, 16, v96
	v_and_b32_e32 v101, 0xffff0000, v96
	v_lshlrev_b32_e32 v52, 16, v64
	v_and_b32_e32 v53, 0xffff0000, v64
	v_pk_mul_f32 v[100:101], v[100:101], v[52:53]
	s_nop 0
	v_cvt_pk_bf16_f32 v64, v100, v101
	v_lshlrev_b32_e32 v100, 16, v97
	v_and_b32_e32 v101, 0xffff0000, v97
	v_lshlrev_b32_e32 v52, 16, v65
	v_and_b32_e32 v53, 0xffff0000, v65
	v_pk_mul_f32 v[100:101], v[100:101], v[52:53]
	s_nop 0
	v_cvt_pk_bf16_f32 v65, v100, v101
	v_lshlrev_b32_e32 v100, 16, v98
	v_and_b32_e32 v101, 0xffff0000, v98
	v_lshlrev_b32_e32 v52, 16, v66
	v_and_b32_e32 v53, 0xffff0000, v66
	v_pk_mul_f32 v[100:101], v[100:101], v[52:53]
	s_nop 0
	v_cvt_pk_bf16_f32 v66, v100, v101
	v_lshlrev_b32_e32 v100, 16, v99
	v_and_b32_e32 v101, 0xffff0000, v99
	v_lshlrev_b32_e32 v52, 16, v67
	v_and_b32_e32 v53, 0xffff0000, v67
	v_pk_mul_f32 v[100:101], v[100:101], v[52:53]
	s_nop 0
	v_cvt_pk_bf16_f32 v67, v100, v101
	global_store_dwordx4 v129, v[64:67], s[88:89] offset:32
	s_waitcnt vmcnt(9) lgkmcnt(0)
	v_lshlrev_b32_e32 v100, 16, v44
	v_and_b32_e32 v101, 0xffff0000, v44
	v_lshlrev_b32_e32 v52, 16, v68
	v_and_b32_e32 v53, 0xffff0000, v68
	v_pk_mul_f32 v[100:101], v[100:101], v[52:53]
	s_nop 0
	v_cvt_pk_bf16_f32 v68, v100, v101
	v_lshlrev_b32_e32 v100, 16, v45
	v_and_b32_e32 v101, 0xffff0000, v45
	v_lshlrev_b32_e32 v52, 16, v69
	v_and_b32_e32 v53, 0xffff0000, v69
	v_pk_mul_f32 v[100:101], v[100:101], v[52:53]
	s_nop 0
	v_cvt_pk_bf16_f32 v69, v100, v101
	v_lshlrev_b32_e32 v100, 16, v46
	v_and_b32_e32 v101, 0xffff0000, v46
	v_lshlrev_b32_e32 v52, 16, v70
	v_and_b32_e32 v53, 0xffff0000, v70
	v_pk_mul_f32 v[100:101], v[100:101], v[52:53]
	s_nop 0
	v_cvt_pk_bf16_f32 v70, v100, v101
	v_lshlrev_b32_e32 v100, 16, v47
	v_and_b32_e32 v101, 0xffff0000, v47
	v_lshlrev_b32_e32 v52, 16, v71
	v_and_b32_e32 v53, 0xffff0000, v71
	v_pk_mul_f32 v[100:101], v[100:101], v[52:53]
	s_nop 0
	v_cvt_pk_bf16_f32 v71, v100, v101
	global_store_dwordx4 v129, v[68:71], s[88:89] offset:48
	s_nop 1
	global_load_dwordx4 v[56:59], v251, s[10:11]
	global_load_dwordx4 v[60:63], v251, s[12:13]
	global_load_dwordx4 v[64:67], v251, s[14:15]
	global_load_dwordx4 v[68:71], v252, s[10:11]
	global_load_dwordx4 v[44:47], v252, s[12:13]
	global_load_dwordx4 v[48:51], v252, s[14:15]
	s_waitcnt vmcnt(13)
; __device__ __forceinline__ unsigned pk2(float lo, float hi) { const f32x2_t v = {lo, hi}; const bf16v2_t b = __builtin_convertvector(v, bf16v2_t); return __builtin_bit_cast(unsigned, b); }
; __device__ __forceinline__ float bflo(unsigned u) { return __uint_as_float(u << 16); }
; __device__ __forceinline__ float bfhi(unsigned u) { return __uint_as_float(u & 0xffff0000u); }
; __device__ __forceinline__ void ret_out_phase(const Args& A, Frame& F, int l, bool lastl, bf16_t* ARET, bf16_t* ALRU) {
;     ...
; #pragma unroll
;         for (int i = 0; i < 4; ++i) {
;             const int u = tid + i * NTHREADS, r = u >> 4, c8 = (u & 15) * 8;
;             const size_t o = (rowbase + r) * D + 128 * h + c8;
;             const u32x4 hf = *(const u32x4*)(WSB(WS_HF) + o), hb = *(const u32x4*)(WSB(WS_HB) + o), gg = *(const u32x4*)(WSB(WS_GG) + o);
;             u32x4 ov;
; #pragma unroll
;             for (int e = 0; e < 4; ++e) ov[e] = pk2((bflo(hf[e]) + bflo(hb[e])) * bflo(gg[e]), (bfhi(hf[e]) + bfhi(hb[e])) * bfhi(gg[e]));
;             *(u32x4*)(ALRU + o) = ov;
;         }
	v_lshlrev_b32_e32 v100, 16, v72
	v_and_b32_e32 v101, 0xffff0000, v72
	v_lshlrev_b32_e32 v52, 16, v76
	v_and_b32_e32 v53, 0xffff0000, v76
	v_pk_add_f32 v[100:101], v[100:101], v[52:53]
	v_lshlrev_b32_e32 v52, 16, v80
	v_and_b32_e32 v53, 0xffff0000, v80
	v_pk_mul_f32 v[100:101], v[100:101], v[52:53]
	s_nop 0
	v_cvt_pk_bf16_f32 v72, v100, v101
	v_lshlrev_b32_e32 v100, 16, v73
	v_and_b32_e32 v101, 0xffff0000, v73
	v_lshlrev_b32_e32 v52, 16, v77
	v_and_b32_e32 v53, 0xffff0000, v77
	v_pk_add_f32 v[100:101], v[100:101], v[52:53]
	v_lshlrev_b32_e32 v52, 16, v81
	v_and_b32_e32 v53, 0xffff0000, v81
	v_pk_mul_f32 v[100:101], v[100:101], v[52:53]
	s_nop 0
	v_cvt_pk_bf16_f32 v73, v100, v101
	v_lshlrev_b32_e32 v100, 16, v74
	v_and_b32_e32 v101, 0xffff0000, v74
	v_lshlrev_b32_e32 v52, 16, v78
	v_and_b32_e32 v53, 0xffff0000, v78
	v_pk_add_f32 v[100:101], v[100:101], v[52:53]
	v_lshlrev_b32_e32 v52, 16, v82
	v_and_b32_e32 v53, 0xffff0000, v82
	v_pk_mul_f32 v[100:101], v[100:101], v[52:53]
	s_nop 0
	v_cvt_pk_bf16_f32 v74, v100, v101
	v_lshlrev_b32_e32 v100, 16, v75
	v_and_b32_e32 v101, 0xffff0000, v75
	v_lshlrev_b32_e32 v52, 16, v79
	v_and_b32_e32 v53, 0xffff0000, v79
	v_pk_add_f32 v[100:101], v[100:101], v[52:53]
	v_lshlrev_b32_e32 v52, 16, v83
	v_and_b32_e32 v53, 0xffff0000, v83
	v_pk_mul_f32 v[100:101], v[100:101], v[52:53]
	s_nop 0
	v_cvt_pk_bf16_f32 v75, v100, v101
	global_store_dwordx4 v141, v[72:75], s[90:91]
	s_waitcnt vmcnt(11)
	v_lshlrev_b32_e32 v100, 16, v84
	v_and_b32_e32 v101, 0xffff0000, v84
	v_lshlrev_b32_e32 v52, 16, v88
	v_and_b32_e32 v53, 0xffff0000, v88
	v_pk_add_f32 v[100:101], v[100:101], v[52:53]
	v_lshlrev_b32_e32 v52, 16, v92
	v_and_b32_e32 v53, 0xffff0000, v92
	v_pk_mul_f32 v[100:101], v[100:101], v[52:53]
	s_nop 0
	v_cvt_pk_bf16_f32 v84, v100, v101
	v_lshlrev_b32_e32 v100, 16, v85
	v_and_b32_e32 v101, 0xffff0000, v85
	v_lshlrev_b32_e32 v52, 16, v89
	v_and_b32_e32 v53, 0xffff0000, v89
	v_pk_add_f32 v[100:101], v[100:101], v[52:53]
	v_lshlrev_b32_e32 v52, 16, v93
	v_and_b32_e32 v53, 0xffff0000, v93
	v_pk_mul_f32 v[100:101], v[100:101], v[52:53]
	s_nop 0
	v_cvt_pk_bf16_f32 v85, v100, v101
	v_lshlrev_b32_e32 v100, 16, v86
	v_and_b32_e32 v101, 0xffff0000, v86
	v_lshlrev_b32_e32 v52, 16, v90
	v_and_b32_e32 v53, 0xffff0000, v90
	v_pk_add_f32 v[100:101], v[100:101], v[52:53]
	v_lshlrev_b32_e32 v52, 16, v94
	v_and_b32_e32 v53, 0xffff0000, v94
	v_pk_mul_f32 v[100:101], v[100:101], v[52:53]
	s_nop 0
	v_cvt_pk_bf16_f32 v86, v100, v101
	v_lshlrev_b32_e32 v100, 16, v87
	v_and_b32_e32 v101, 0xffff0000, v87
	v_lshlrev_b32_e32 v52, 16, v91
	v_and_b32_e32 v53, 0xffff0000, v91
	v_pk_add_f32 v[100:101], v[100:101], v[52:53]
	v_lshlrev_b32_e32 v52, 16, v95
	v_and_b32_e32 v53, 0xffff0000, v95
	v_pk_mul_f32 v[100:101], v[100:101], v[52:53]
	s_nop 0
	v_cvt_pk_bf16_f32 v87, v100, v101
	global_store_dwordx4 v250, v[84:87], s[90:91]
	s_waitcnt vmcnt(5)
	v_lshlrev_b32_e32 v100, 16, v56
	v_and_b32_e32 v101, 0xffff0000, v56
	v_lshlrev_b32_e32 v52, 16, v60
	v_and_b32_e32 v53, 0xffff0000, v60
	v_pk_add_f32 v[100:101], v[100:101], v[52:53]
	v_lshlrev_b32_e32 v52, 16, v64
	v_and_b32_e32 v53, 0xffff0000, v64
	v_pk_mul_f32 v[100:101], v[100:101], v[52:53]
	s_nop 0
	v_cvt_pk_bf16_f32 v56, v100, v101
	v_lshlrev_b32_e32 v100, 16, v57
	v_and_b32_e32 v101, 0xffff0000, v57
	v_lshlrev_b32_e32 v52, 16, v61
	v_and_b32_e32 v53, 0xffff0000, v61
	v_pk_add_f32 v[100:101], v[100:101], v[52:53]
	v_lshlrev_b32_e32 v52, 16, v65
	v_and_b32_e32 v53, 0xffff0000, v65
	v_pk_mul_f32 v[100:101], v[100:101], v[52:53]
	s_nop 0
	v_cvt_pk_bf16_f32 v57, v100, v101
	v_lshlrev_b32_e32 v100, 16, v58
	v_and_b32_e32 v101, 0xffff0000, v58
	v_lshlrev_b32_e32 v52, 16, v62
	v_and_b32_e32 v53, 0xffff0000, v62
	v_pk_add_f32 v[100:101], v[100:101], v[52:53]
	v_lshlrev_b32_e32 v52, 16, v66
	v_and_b32_e32 v53, 0xffff0000, v66
	v_pk_mul_f32 v[100:101], v[100:101], v[52:53]
	s_nop 0
	v_cvt_pk_bf16_f32 v58, v100, v101
	v_lshlrev_b32_e32 v100, 16, v59
	v_and_b32_e32 v101, 0xffff0000, v59
	v_lshlrev_b32_e32 v52, 16, v63
	v_and_b32_e32 v53, 0xffff0000, v63
	v_pk_add_f32 v[100:101], v[100:101], v[52:53]
	v_lshlrev_b32_e32 v52, 16, v67
	v_and_b32_e32 v53, 0xffff0000, v67
	v_pk_mul_f32 v[100:101], v[100:101], v[52:53]
	s_nop 0
	v_cvt_pk_bf16_f32 v59, v100, v101
	global_store_dwordx4 v251, v[56:59], s[90:91]
	s_waitcnt vmcnt(3)
	v_lshlrev_b32_e32 v100, 16, v68
	v_and_b32_e32 v101, 0xffff0000, v68
	v_lshlrev_b32_e32 v52, 16, v44
	v_and_b32_e32 v53, 0xffff0000, v44
	v_pk_add_f32 v[100:101], v[100:101], v[52:53]
	v_lshlrev_b32_e32 v52, 16, v48
	v_and_b32_e32 v53, 0xffff0000, v48
	v_pk_mul_f32 v[100:101], v[100:101], v[52:53]
	s_nop 0
	v_cvt_pk_bf16_f32 v68, v100, v101
	v_lshlrev_b32_e32 v100, 16, v69
	v_and_b32_e32 v101, 0xffff0000, v69
	v_lshlrev_b32_e32 v52, 16, v45
	v_and_b32_e32 v53, 0xffff0000, v45
	v_pk_add_f32 v[100:101], v[100:101], v[52:53]
	v_lshlrev_b32_e32 v52, 16, v49
	v_and_b32_e32 v53, 0xffff0000, v49
	v_pk_mul_f32 v[100:101], v[100:101], v[52:53]
	s_nop 0
	v_cvt_pk_bf16_f32 v69, v100, v101
	v_lshlrev_b32_e32 v100, 16, v70
	v_and_b32_e32 v101, 0xffff0000, v70
	v_lshlrev_b32_e32 v52, 16, v46
	v_and_b32_e32 v53, 0xffff0000, v46
	v_pk_add_f32 v[100:101], v[100:101], v[52:53]
	v_lshlrev_b32_e32 v52, 16, v50
	v_and_b32_e32 v53, 0xffff0000, v50
	v_pk_mul_f32 v[100:101], v[100:101], v[52:53]
	s_nop 0
	v_cvt_pk_bf16_f32 v70, v100, v101
	v_lshlrev_b32_e32 v100, 16, v71
	v_and_b32_e32 v101, 0xffff0000, v71
	v_lshlrev_b32_e32 v52, 16, v47
	v_and_b32_e32 v53, 0xffff0000, v47
	v_pk_add_f32 v[100:101], v[100:101], v[52:53]
	v_lshlrev_b32_e32 v52, 16, v51
	v_and_b32_e32 v53, 0xffff0000, v51
	v_pk_mul_f32 v[100:101], v[100:101], v[52:53]
	s_nop 0
	v_cvt_pk_bf16_f32 v71, v100, v101
	global_store_dwordx4 v252, v[68:71], s[90:91]
	s_cbranch_scc1 .LBB0_30

; __device__ __forceinline__ void norm_phase(const Args& A, Frame& F, int l, int s, bool latonly, bool tailsum) {
;     ...
;     for (; row < MROWS; row += stride) {
;         u32x2 cx[4];
; #pragma unroll
;         for (int j = 0; j < 4; ++j) cx[j] = nx[j];
;         { const int rn = row + stride < MROWS ? row + stride : row;
;           const u32x2* xrn = (const u32x2*)(WSB(WS_R) + (size_t)rn * D) + F.lane;
; #pragma unroll
;           for (int j = 0; j < 4; ++j) nx[j] = xrn[64 * j]; }
;         const int b = row / TB, p = row - b * TB, mr = p < CTXL ? 8 : b;
;         if (latonly && p < CTXL) continue;
;         f32x4 v[4]; float ss = 0.f;
; #pragma unroll
;         for (int j = 0; j < 4; ++j) { const u32x2 xv = cx[j]; v[j][0] = bflo(xv.x); v[j][1] = bfhi(xv.x); v[j][2] = bflo(xv.y); v[j][3] = bfhi(xv.y); }
;         if (tailsum && row >= 16384) {
; #pragma unroll
;             for (int sp = 0; sp < 8; ++sp) {
;                 const u32x2* pr = (const u32x2*)(WSB(WS_PART) + ((size_t)sp * 2048 + (row - 16384)) * D) + F.lane;
; #pragma unroll
;                 for (int j = 0; j < 4; ++j) { const u32x2 pv = pr[64 * j]; v[j][0] += bflo(pv.x); v[j][1] += bfhi(pv.x); v[j][2] += bflo(pv.y); v[j][3] += bfhi(pv.y); }
;             }
;             u32x2* xw = (u32x2*)(WSB(WS_R) + (size_t)row * D) + F.lane;
; #pragma unroll
;             for (int j = 0; j < 4; ++j) { u32x2 o; o.x = pk2(v[j][0], v[j][1]); o.y = pk2(v[j][2], v[j][3]); xw[64 * j] = o; v[j][0] = bflo(o.x); v[j][1] = bfhi(o.x); v[j][2] = bflo(o.y); v[j][3] = bfhi(o.y); }
;         }
; #pragma unroll
;         for (int j = 0; j < 4; ++j) ss += (v[j][0] * v[j][0] + v[j][1] * v[j][1]) + (v[j][2] * v[j][2] + v[j][3] * v[j][3]);
;         const float rstd = rsqrtf(wave_sum(ss) * (1.f / D) + EPS);
;         const float* mp = WSF(WS_MODS) + (size_t)(l * 9 + mr) * NMOD + (size_t)(3 * s) * D;
;         u32x2* o8 = (u32x2*)(WSB(WS_AN) + (size_t)row * D) + F.lane;
; #pragma unroll
;         for (int j = 0; j < 4; ++j) {
;             const int col = 4 * (F.lane + 64 * j);
;             const f32x4 gv = gvh[j], sh = *(const f32x4*)(mp + col), sc = *(const f32x4*)(mp + D + col);
;             const f32x4 y = (v[j] * rstd * gv) * (sc + 1.f) + sh;
;             u32x2 o; o.x = pk2(y[0], y[1]); o.y = pk2(y[2], y[3]);
;             o8[64 * j] = o;
;         }
;     }
.LBB0_693:
	s_and_b64 s[40:41], s[40:41], exec
	s_cselect_b32 s4, 8, s4
	s_add_i32 s4, s4, s29
	s_mul_hi_i32 s5, s4, 0x9000
	s_mul_i32 s4, s4, 0x9000
	s_add_u32 s4, s2, s4
	s_addc_u32 s5, s20, s5
	s_add_u32 s40, s4, 0x1000
	s_addc_u32 s41, s5, 0
	global_load_dwordx4 v[192:195], v0, s[40:41]
	global_load_dwordx4 v[196:199], v0, s[4:5]
	global_load_dwordx4 v[200:203], v103, s[40:41]
	global_load_dwordx4 v[204:207], v0, s[4:5] offset:1024
	global_load_dwordx4 v[208:211], v112, s[40:41]
	global_load_dwordx4 v[212:215], v0, s[4:5] offset:2048
	global_load_dwordx4 v[216:219], v113, s[40:41]
	global_load_dwordx4 v[220:223], v0, s[4:5] offset:3072
	s_cmpk_lt_i32 s7, 0x4800
	s_cselect_b32 s4, s7, s48
	s_ashr_i32 s5, s4, 31
	s_lshl_b64 s[4:5], s[4:5], 11
	v_lshl_add_u64 v[24:25], v[18:19], 0, s[4:5]
	global_load_dwordx2 v[30:31], v[24:25], off
	global_load_dwordx2 v[28:29], v[24:25], off offset:512
	global_load_dwordx2 v[26:27], v[24:25], off offset:1024
	s_nop 0
	global_load_dwordx2 v[24:25], v[24:25], off offset:1536
	v_pk_mul_f32 v[56:57], v[40:41], v[40:41]
	v_pk_mul_f32 v[58:59], v[42:43], v[42:43]
	v_pk_mul_f32 v[60:61], v[44:45], v[44:45]
	v_pk_mul_f32 v[62:63], v[46:47], v[46:47]
	v_cmp_lt_i32_e32 vcc, v176, v175
	v_pk_mov_b32 v[68:69], v[62:63], v[60:61] op_sel:[1,0]
	v_mov_b32_e32 v63, v61
	v_pk_mov_b32 v[60:61], v[58:59], v[56:57] op_sel:[1,0]
	v_mov_b32_e32 v59, v57
	v_mul_f32_e32 v64, v38, v38
	v_mul_f32_e32 v66, v36, v36
	v_cndmask_b32_e32 v67, v174, v176, vcc
	v_pk_add_f32 v[62:63], v[68:69], v[62:63]
	v_pk_add_f32 v[58:59], v[60:61], v[58:59]
	v_pk_fma_f32 v[56:57], v[38:39], v[38:39], v[64:65] op_sel_hi:[1,1,0]
	v_pk_fma_f32 v[64:65], v[36:37], v[36:37], v[66:67] op_sel_hi:[1,1,0]
	v_pk_add_f32 v[60:61], v[62:63], v[62:63] op_sel_hi:[0,1]
	v_pk_add_f32 v[58:59], v[58:59], v[58:59] op_sel_hi:[0,1]
	v_mul_f32_e32 v56, v34, v34
	v_mul_f32_e32 v64, v35, v35
	v_mul_f32_e32 v60, v32, v32
	v_mul_f32_e32 v58, v33, v33
	v_pk_add_f32 v[56:57], v[56:57], v[64:65]
	v_pk_add_f32 v[58:59], v[60:61], v[58:59]
	v_lshlrev_b32_e32 v66, 2, v67
	v_pk_add_f32 v[56:57], v[56:57], v[58:59]
	v_cmp_lt_i32_e32 vcc, v177, v175
	v_add_f32_e32 v56, v56, v57
	s_nop 1
	v_add_f32_dpp v56, v56, v56 quad_perm:[1,0,3,2] row_mask:0xf bank_mask:0xf
	s_nop 1
	v_add_f32_dpp v56, v56, v56 quad_perm:[2,3,0,1] row_mask:0xf bank_mask:0xf
	s_nop 1
	v_add_f32_dpp v56, v56, v56 row_half_mirror row_mask:0xf bank_mask:0xf
	s_nop 1
	v_add_f32_dpp v56, v56, v56 row_mirror row_mask:0xf bank_mask:0xf
	v_mov_b32_e32 v57, v56
	s_nop 1
	v_permlane16_swap_b32 v56, v57
	v_add_f32_e32 v56, v56, v57
	v_mov_b32_e32 v57, v56
	s_nop 1
	v_permlane32_swap_b32 v56, v57
	v_add_f32_e32 v56, v56, v57
	v_fmamk_f32 v56, v56, 0x3a800000, v170
	v_mul_f32_e32 v57, 0x4b800000, v56
	v_cmp_gt_f32_e32 vcc, s33, v56
	v_pk_mul_f32 v[58:59], v[2:3], v[2:3]
	v_pk_mul_f32 v[60:61], v[4:5], v[4:5]
	v_cndmask_b32_e32 v56, v56, v57, vcc
	v_rsq_f32_e32 v56, v56
	s_nop 0
	v_mul_f32_e32 v57, 0x45800000, v56
	v_cndmask_b32_e32 v56, v56, v57, vcc
	v_pk_mul_f32 v[44:45], v[44:45], v[56:57] op_sel_hi:[1,0]
	v_pk_mul_f32 v[46:47], v[46:47], v[56:57] op_sel_hi:[1,0]
	v_pk_mul_f32 v[44:45], v[4:5], v[44:45]
	v_pk_mul_f32 v[46:47], v[2:3], v[46:47]
	v_pk_mul_f32 v[40:41], v[40:41], v[56:57] op_sel_hi:[1,0]
	v_pk_mul_f32 v[42:43], v[42:43], v[56:57] op_sel_hi:[1,0]
	v_pk_mul_f32 v[40:41], v[8:9], v[40:41]
	v_pk_mul_f32 v[42:43], v[6:7], v[42:43]
	v_pk_mul_f32 v[36:37], v[36:37], v[56:57] op_sel_hi:[1,0]
	v_pk_mul_f32 v[38:39], v[38:39], v[56:57] op_sel_hi:[1,0]
	v_pk_mul_f32 v[36:37], v[12:13], v[36:37]
	v_pk_mul_f32 v[38:39], v[10:11], v[38:39]
	v_pk_mul_f32 v[32:33], v[32:33], v[56:57] op_sel_hi:[1,0]
	v_pk_mul_f32 v[34:35], v[34:35], v[56:57] op_sel_hi:[1,0]
	v_pk_mul_f32 v[32:33], v[16:17], v[32:33]
	v_pk_mul_f32 v[34:35], v[14:15], v[34:35]
	s_waitcnt vmcnt(4)
	v_pk_add_f32 v[194:195], v[194:195], 1.0 op_sel_hi:[1,0]
	v_pk_add_f32 v[192:193], v[192:193], 1.0 op_sel_hi:[1,0]
	v_pk_fma_f32 v[44:45], v[194:195], v[44:45], v[198:199]
	v_pk_fma_f32 v[46:47], v[192:193], v[46:47], v[196:197]
	s_nop 0
	v_cvt_pk_bf16_f32 v46, v46, v47
	v_cvt_pk_bf16_f32 v47, v44, v45
	global_store_dwordx2 v[22:23], v[46:47], off offset:-1024
	v_pk_add_f32 v[202:203], v[202:203], 1.0 op_sel_hi:[1,0]
	v_pk_add_f32 v[200:201], v[200:201], 1.0 op_sel_hi:[1,0]
	v_pk_fma_f32 v[40:41], v[202:203], v[40:41], v[206:207]
	v_pk_fma_f32 v[42:43], v[200:201], v[42:43], v[204:205]
	s_nop 0
	v_cvt_pk_bf16_f32 v42, v42, v43
	v_cvt_pk_bf16_f32 v43, v40, v41
	global_store_dwordx2 v[22:23], v[42:43], off offset:-512
	v_pk_add_f32 v[210:211], v[210:211], 1.0 op_sel_hi:[1,0]
	v_pk_add_f32 v[208:209], v[208:209], 1.0 op_sel_hi:[1,0]
	v_pk_fma_f32 v[36:37], v[210:211], v[36:37], v[214:215]
	v_pk_fma_f32 v[38:39], v[208:209], v[38:39], v[212:213]
	s_nop 0
	v_cvt_pk_bf16_f32 v38, v38, v39
	v_cvt_pk_bf16_f32 v39, v36, v37
	global_store_dwordx2 v[22:23], v[38:39], off
	v_pk_add_f32 v[218:219], v[218:219], 1.0 op_sel_hi:[1,0]
	v_pk_add_f32 v[216:217], v[216:217], 1.0 op_sel_hi:[1,0]
	v_pk_fma_f32 v[32:33], v[218:219], v[32:33], v[222:223]
	v_pk_fma_f32 v[34:35], v[216:217], v[34:35], v[220:221]
	s_nop 0
	v_cvt_pk_bf16_f32 v34, v34, v35
	v_cvt_pk_bf16_f32 v35, v32, v33
	global_store_dwordx2 v[22:23], v[34:35], off offset:512
	v_lshl_add_u64 v[22:23], v[22:23], 0, s[10:11]
	s_and_b64 vcc, exec, s[14:15]
	s_mov_b32 s48, s7
	s_waitcnt vmcnt(4)
	v_mov_b32_e32 v38, v30
	v_mov_b32_e32 v39, v31
	v_mov_b32_e32 v36, v28
	v_mov_b32_e32 v37, v29
	v_mov_b32_e32 v34, v26
	v_mov_b32_e32 v35, v27
	v_mov_b32_e32 v32, v24
	v_mov_b32_e32 v33, v25
	s_cbranch_vccnz .LBB0_698
	s_branch .LBB0_695
